# ssd_sample: state elements remapped so every state load/store covers full 128-B row segments (n = 32*e4 + 4*nq + j)
# baseline (speedup 1.0000x reference)
.LBB0_677:
	s_waitcnt vmcnt(0)
	s_barrier
	s_mov_b64 s[2:3], -1
	v_readfirstlane_b32 s94, v157
	s_ashr_i32 s95, s94, 6
	v_and_b32_e32 v159, 63, v157
	s_cmpk_gt_i32 s93, 0xff
	s_cbranch_scc0 .LBB0_752
	s_add_i32 s2, s93, 0xffffff00
	s_lshr_b32 s18, s2, 1
	s_and_b32 s96, s93, 1
	s_add_i32 s6, s18, s28
	s_lshl_b32 s2, s6, 4
	s_lshl_b32 s12, s96, 3
	s_or_b32 s2, s2, s12
	s_ashr_i32 s3, s2, 31
	v_readlane_b32 s40, v254, 33
	s_lshl_b32 s66, s18, 2
	v_ashrrev_i32_e32 v0, 3, v157
	s_lshl_b64 s[2:3], s[2:3], 15
	v_readlane_b32 s50, v254, 43
	v_ashrrev_i32_e32 v1, 31, v0
	v_readlane_b32 s51, v254, 44
	s_add_u32 s2, s50, s2
	v_and_b32_e32 v64, 7, v157
	s_addc_u32 s3, s51, s3
	v_lshlrev_b64 v[52:53], 9, v[0:1]
	v_lshl_add_u64 v[4:5], s[2:3], 0, v[52:53]
	v_lshlrev_b32_e32 v2, 4, v64
	v_lshl_add_u64 v[12:13], v[4:5], 0, v[2:3]
	v_add_co_u32_e32 v14, vcc, 0x8000, v12
	s_mov_b64 s[2:3], 0x8000
	s_nop 0
	v_addc_co_u32_e32 v15, vcc, 0, v13, vcc
	v_lshl_add_u64 v[28:29], v[12:13], 0, s[2:3]
	s_mov_b64 s[2:3], 0x10000
	v_add_co_u32_e32 v16, vcc, 0x10000, v12
	v_lshl_add_u64 v[32:33], v[12:13], 0, s[2:3]
	s_nop 0
	v_addc_co_u32_e32 v17, vcc, 0, v13, vcc
	global_load_dwordx4 v[36:39], v[12:13], off offset:384
	global_load_dwordx4 v[40:43], v[12:13], off offset:256
	global_load_dwordx4 v[44:47], v[12:13], off offset:128
	global_load_dwordx4 v[48:51], v[12:13], off
	global_load_dwordx4 v[4:7], v[28:29], off offset:256
	global_load_dwordx4 v[8:11], v[28:29], off offset:128
	s_nop 0
	global_load_dwordx4 v[12:15], v[14:15], off
	s_nop 0
	global_load_dwordx4 v[16:19], v[16:17], off
	s_nop 0
	global_load_dwordx4 v[20:23], v[32:33], off offset:384
	global_load_dwordx4 v[24:27], v[32:33], off offset:256
	s_nop 0
	global_load_dwordx4 v[28:31], v[28:29], off offset:384
	s_nop 0
	global_load_dwordx4 v[32:35], v[32:33], off offset:128
	v_cndmask_b32_e64 v65, 0, 1, s[76:77]
	s_movk_i32 s2, 0x300
	v_readfirstlane_b32 s57, v65
	s_or_b32 s97, s66, 0x8000
	v_cmp_gt_i32_e32 vcc, s2, v157
	v_readlane_b32 s41, v254, 34
	v_readlane_b32 s42, v254, 35
	v_readlane_b32 s43, v254, 36
	v_readlane_b32 s44, v254, 37
	v_readlane_b32 s45, v254, 38
	v_readlane_b32 s46, v254, 39
	v_readlane_b32 s47, v254, 40
	v_readlane_b32 s48, v254, 41
	v_readlane_b32 s49, v254, 42
	v_readlane_b32 s52, v254, 45
	v_readlane_b32 s53, v254, 46
	v_readlane_b32 s54, v254, 47
	v_readlane_b32 s55, v254, 48
	s_and_saveexec_b64 s[2:3], vcc
	s_cbranch_execz .LBB0_721
	s_lshl_b32 s13, s57, 7
	s_lshl_b32 s14, s96, 7
	v_readlane_b32 s20, v254, 53
	s_addk_i32 s13, 0x280
	s_bitset1_b32 s14, 9
	s_lshl_b32 s15, s96, 9
	s_mul_i32 s38, s6, 0x4800
	v_readlane_b32 s22, v254, 55
	s_mul_hi_i32 s39, s6, 0x4800
	v_readlane_b32 s23, v254, 56
	s_add_u32 s24, s22, s38
	s_addc_u32 s25, s23, s39
	v_readlane_b32 s21, v254, 54
	s_add_u32 s6, s24, 0xa724000
	s_mul_i32 s8, s97, 0xd00
	s_addc_u32 s7, s25, 0
	s_lshl_b64 s[16:17], s[8:9], 1
	v_readlane_b32 s20, v255, 24
	v_readlane_b32 s21, v255, 25
	s_add_u32 s50, s20, s16
	s_mul_i32 s8, s18, 0x3400
	s_addc_u32 s51, s21, s17
	s_lshl_b64 s[18:19], s[8:9], 1
	s_add_u32 s8, s20, s18
	s_addc_u32 s18, s21, s19
	s_add_u32 s40, s8, 0xd002800
	s_addc_u32 s41, s18, 0
	s_add_u32 s42, s8, 0xd004200
	s_addc_u32 s43, s18, 0
	s_add_u32 s44, s8, 0xd005c00
	s_addc_u32 s45, s18, 0
	s_add_u32 s46, s24, 0xa725800
	s_addc_u32 s47, s25, 0
	s_add_u32 s48, s24, 0xa727000
	s_addc_u32 s49, s25, 0
	s_mov_b32 s8, s28
	s_mov_b32 s52, s29
	s_mov_b32 s53, s26
	s_mov_b32 s54, s27
	v_readlane_b32 s16, v254, 33
	v_readlane_b32 s24, v254, 41
	v_readlane_b32 s29, v254, 46
	v_readlane_b32 s25, v254, 42
	v_readlane_b32 s26, v254, 43
	v_readlane_b32 s27, v254, 44
	v_readlane_b32 s28, v254, 45
	v_readlane_b32 s30, v254, 47
	v_readlane_b32 s31, v254, 48
	s_mov_b32 s29, s52
	s_add_u32 s52, s24, s38
	s_mov_b32 s27, s54
	s_mov_b32 s26, s53
	s_mov_b32 s28, s8
	s_mov_b32 s31, 0x16000
	s_movk_i32 s30, 0x2000
	s_addc_u32 s53, s25, s39
	v_lshl_add_u32 v58, v157, 2, 0
	s_mov_b64 s[88:89], 0
	v_mov_b32_e32 v59, v157
	v_readlane_b32 s17, v254, 34
	v_readlane_b32 s18, v254, 35
	v_readlane_b32 s19, v254, 36
	v_readlane_b32 s20, v254, 37
	v_readlane_b32 s21, v254, 38
	v_readlane_b32 s22, v254, 39
	v_readlane_b32 s23, v254, 40
	s_branch .LBB0_681

.LBB0_735:
	s_or_b64 exec, exec, s[2:3]
	s_and_saveexec_b64 s[2:3], vcc
	v_mov_b32_e32 v54, s16
	ds_write_b32 v54, v55 offset:12384
	s_or_b64 exec, exec, s[2:3]
	s_lshr_b32 s8, s11, 1
	s_lshl_b32 s2, s8, 4
	v_readlane_b32 s3, v255, 26
	s_add_i32 s2, s3, s2
	s_lshl_b32 s12, s57, 3
	s_add_i32 s2, s2, s12
	s_ashr_i32 s3, s2, 31
	s_lshl_b64 s[6:7], s[2:3], 15
	s_mulk_i32 s8, 0x3400
	s_lshl_b32 s2, s57, 9
	s_or_b32 s13, s8, s2
	s_add_i32 s2, s10, s12
	s_add_i32 s8, s13, 0x6801000
	s_ashr_i32 s3, s2, 31
	s_lshl_b64 s[14:15], s[8:9], 1
	s_add_i32 s22, s13, 0x6801d00
	s_lshl_b64 s[2:3], s[2:3], 2
	s_add_u32 s2, s86, s2
	s_addc_u32 s3, s87, s3
	s_add_i32 s8, s13, 0x6800000
	s_lshl_b64 s[16:17], s[8:9], 1
	s_add_i32 s8, s13, 0x6802a00
	v_lshl_add_u64 v[52:53], s[6:7], 0, v[52:53]
	v_readlane_b32 s6, v255, 33
	s_lshl_b64 s[18:19], s[8:9], 1
	v_readlane_b32 s20, v255, 24
	v_lshl_add_u64 v[52:53], v[52:53], 0, v[2:3]
	v_readlane_b32 s7, v255, 34
	v_lshlrev_b32_e32 v54, 5, v65
	v_mov_b32_e32 v55, v3
	v_readlane_b32 s21, v255, 25
	v_lshl_add_u64 v[140:141], s[6:7], 0, v[52:53]
	s_add_u32 s6, s20, s14
	v_lshl_add_u64 v[128:129], s[60:61], 0, v[54:55]
	v_lshlrev_b64 v[54:55], 1, v[0:1]
	s_addc_u32 s7, s21, s15
	v_lshl_add_u64 v[142:143], s[6:7], 0, v[54:55]
	s_add_u32 s6, s26, s16
	s_addc_u32 s7, s27, s17
	v_lshlrev_b32_e32 v185, 2, v0
	v_lshl_add_u64 v[0:1], s[6:7], 0, v[54:55]
	s_add_u32 s6, s20, s18
	s_addc_u32 s7, s21, s19
	v_cmp_eq_u32_e32 vcc, 0, v64
	v_mov_b32_e32 v137, v66
	v_lshl_add_u64 v[130:131], s[20:21], 0, v[54:55]
	v_lshl_add_u64 v[144:145], s[84:85], 0, v[52:53]
	v_lshl_add_u64 v[146:147], s[6:7], 0, v[54:55]
	s_mov_b32 s12, 0
	s_movk_i32 s13, 0x3000
	s_mov_b64 s[6:7], 0
	s_mov_b32 s8, s22
	v_and_b32_e32 v70, 7, v157
	v_lshlrev_b32_e32 v70, 7, v70
	v_mov_b32_e32 v71, 0
	v_lshl_add_u64 v[68:69], v[0:1], 0, v[70:71]
	global_load_ushort v209, v[68:69], off
	v_lshl_add_u64 v[68:69], v[142:143], 0, v[70:71]
	global_load_ushort v188, v[68:69], off
	v_lshl_add_u64 v[68:69], s[8:9], 1, v[130:131]
	v_lshl_add_u64 v[68:69], v[68:69], 0, v[70:71]
	global_load_ushort v187, v[68:69], off
	v_lshl_add_u64 v[68:69], v[146:147], 0, v[70:71]
	global_load_ushort v186, v[68:69], off
	s_waitcnt lgkmcnt(0)
	s_barrier
	global_load_dwordx4 v[52:55], v[144:145], off offset:352
	global_load_dwordx4 v[56:59], v[144:145], off offset:224
	global_load_dwordx4 v[60:63], v[144:145], off offset:96
	global_load_dwordx4 v[64:67], v[144:145], off offset:-32
	s_lshl_b32 s14, s57, 5
	s_add_u32 s14, s60, s14
	s_addc_u32 s15, s61, 0
	s_nop 0
	s_load_dword s12, s[2:3], 0x0
	s_load_dword s14, s[14:15], 0x0
	v_and_b32_e32 v2, 7, v157
	v_cmp_eq_u32_e32 vcc, 0, v2
	v_add_u32_e32 v189, 0, v185
	s_waitcnt lgkmcnt(0)
	v_mov_b32_e32 v2, s14
	s_mov_b32 s14, 0x3fb8aa3b
	s_waitcnt vmcnt(8)
	v_mul_f32_e32 v68, 0x3fb8aa3b, v2
	v_fma_f32 v69, v2, s14, -v68
	v_rndne_f32_e32 v70, v68
	v_fmac_f32_e32 v69, 0x32a5705f, v2
	v_sub_f32_e32 v68, v68, v70
	v_add_f32_e32 v68, v68, v69
	v_exp_f32_e32 v68, v68
	v_cvt_i32_f32_e32 v69, v70
	s_mov_b32 s14, 0xc2ce8ed0
	v_cmp_ngt_f32_e64 s[38:39], s14, v2
	s_mov_b32 s14, 0x42b17218
	v_ldexp_f32 v68, v68, v69
	v_cndmask_b32_e64 v68, 0, v68, s[38:39]
	v_cmp_nlt_f32_e64 s[38:39], s14, v2
	s_add_i32 s14, s13, 0
	v_mov_b32_e32 v72, s14
	v_cndmask_b32_e64 v116, v203, v68, s[38:39]
	ds_read2_b32 v[68:69], v72 offset1:8
	ds_read2st64_b32 v[70:71], v189 offset1:8
	ds_read_b128 v[104:107], v137 offset:10240
	ds_read_b128 v[112:115], v137 offset:10368
	ds_read_b128 v[120:123], v137 offset:10496
	ds_read_b128 v[108:111], v137 offset:10624
	s_waitcnt lgkmcnt(5)
	v_mul_f32_e64 v2, v68, -v116
	s_waitcnt lgkmcnt(4)
	v_mul_f32_e32 v156, v68, v70
	v_mul_f32_e64 v68, v69, -v116
	v_mul_f32_e32 v68, 0x3fb8aa3b, v68
	v_exp_f32_e32 v158, v68
	v_mul_f32_e32 v160, v69, v71
	ds_read_b128 v[100:103], v137 offset:10752
	ds_read_b128 v[96:99], v137 offset:10880
	ds_read_b128 v[92:95], v137 offset:11008
	ds_read_b128 v[88:91], v137 offset:11136
	ds_read2_b32 v[68:69], v72 offset0:16 offset1:24
	v_mul_f32_e32 v2, 0x3fb8aa3b, v2
	v_exp_f32_e32 v2, v2
	s_waitcnt lgkmcnt(0)
	v_mul_f32_e64 v70, v68, -v116
	v_mul_f32_e32 v70, 0x3fb8aa3b, v70
	v_exp_f32_e32 v162, v70
	ds_read2st64_b32 v[70:71], v189 offset0:16 offset1:24
	ds_read_b128 v[84:87], v137 offset:11264
	ds_read_b128 v[80:83], v137 offset:11392
	ds_read_b128 v[76:79], v137 offset:11520
	ds_read_b128 v[72:75], v137 offset:11648
	s_waitcnt lgkmcnt(4)
	v_mul_f32_e32 v164, v68, v70
	v_mul_f32_e64 v68, v69, -v116
	v_mul_f32_e32 v68, 0x3fb8aa3b, v68
	v_exp_f32_e32 v166, v68
	v_mul_f32_e32 v168, v69, v71
	ds_read_b128 v[68:71], v137 offset:11776
	ds_read_b128 v[148:151], v137 offset:8192
	ds_read_b128 v[170:173], v137 offset:8320
	ds_read_b128 v[124:127], v137 offset:8448
	ds_read_b128 v[116:119], v137 offset:8576
	ds_read_b128 v[152:155], v137 offset:8704
	ds_read_b128 v[174:177], v137 offset:9216
	s_waitcnt lgkmcnt(5)
	v_pk_mul_f32 v[148:149], v[156:157], v[148:149] op_sel_hi:[0,1]
	v_pk_fma_f32 v[48:49], v[48:49], v[2:3], v[148:149] op_sel_hi:[1,0,1]
	s_waitcnt lgkmcnt(4)
	v_pk_mul_f32 v[170:171], v[156:157], v[170:171] op_sel_hi:[0,1]
	v_fma_f32 v210, v48, v104, 0
	v_fmac_f32_e32 v210, v49, v105
	s_waitcnt lgkmcnt(1)
	v_pk_mul_f32 v[104:105], v[160:161], v[152:153] op_sel_hi:[0,1]
	v_pk_fma_f32 v[152:153], v[48:49], v[158:159], v[104:105] op_sel_hi:[1,0,1]
	v_pk_mul_f32 v[104:105], v[156:157], v[150:151] op_sel_hi:[0,1]
	v_pk_fma_f32 v[50:51], v[50:51], v[2:3], v[104:105] op_sel_hi:[1,0,1]
	v_pk_fma_f32 v[44:45], v[44:45], v[2:3], v[170:171] op_sel_hi:[1,0,1]
	v_fmac_f32_e32 v210, v50, v106
	v_fmac_f32_e32 v210, v51, v107
	v_fmac_f32_e32 v210, v44, v112
	v_fmac_f32_e32 v210, v45, v113
	v_pk_mul_f32 v[112:113], v[156:157], v[172:173] op_sel_hi:[0,1]
	v_pk_fma_f32 v[46:47], v[46:47], v[2:3], v[112:113] op_sel_hi:[1,0,1]
	v_pk_mul_f32 v[124:125], v[156:157], v[124:125] op_sel_hi:[0,1]
	v_fmac_f32_e32 v210, v46, v114
	v_fmac_f32_e32 v210, v47, v115
	v_pk_fma_f32 v[40:41], v[40:41], v[2:3], v[124:125] op_sel_hi:[1,0,1]
	ds_read_b128 v[178:181], v137 offset:9728
	ds_read_b128 v[212:215], v137 offset:9856
	v_fmac_f32_e32 v210, v40, v120
	v_fmac_f32_e32 v210, v41, v121
	v_pk_mul_f32 v[120:121], v[156:157], v[126:127] op_sel_hi:[0,1]
	v_pk_fma_f32 v[42:43], v[42:43], v[2:3], v[120:121] op_sel_hi:[1,0,1]
	v_pk_mul_f32 v[116:117], v[156:157], v[116:117] op_sel_hi:[0,1]
	v_fmac_f32_e32 v210, v42, v122
	v_fmac_f32_e32 v210, v43, v123
	v_pk_fma_f32 v[36:37], v[36:37], v[2:3], v[116:117] op_sel_hi:[1,0,1]
	v_pk_mul_f32 v[104:105], v[160:161], v[154:155] op_sel_hi:[0,1]
	v_fmac_f32_e32 v210, v36, v108
	s_waitcnt lgkmcnt(2)
	v_pk_mul_f32 v[48:49], v[164:165], v[174:175] op_sel_hi:[0,1]
	v_pk_fma_f32 v[154:155], v[50:51], v[158:159], v[104:105] op_sel_hi:[1,0,1]
	v_pk_mul_f32 v[104:105], v[164:165], v[176:177] op_sel_hi:[0,1]
	ds_read_b128 v[174:177], v137 offset:8832
	v_fmac_f32_e32 v210, v37, v109
	v_pk_mul_f32 v[108:109], v[156:157], v[118:119] op_sel_hi:[0,1]
	v_pk_fma_f32 v[148:149], v[152:153], v[162:163], v[48:49] op_sel_hi:[1,0,1]
	s_waitcnt lgkmcnt(2)
	v_pk_mul_f32 v[48:49], v[168:169], v[178:179] op_sel_hi:[0,1]
	v_pk_mul_f32 v[50:51], v[168:169], v[180:181] op_sel_hi:[0,1]
	ds_read_b128 v[178:181], v137 offset:9344
	v_pk_fma_f32 v[38:39], v[38:39], v[2:3], v[108:109] op_sel_hi:[1,0,1]
	s_waitcnt lgkmcnt(1)
	v_pk_mul_f32 v[170:171], v[160:161], v[174:175] op_sel_hi:[0,1]
	v_fmac_f32_e32 v210, v38, v110
	v_fmac_f32_e32 v210, v39, v111
	ds_bpermute_b32 v2, v161, v210
	v_pk_mul_f32 v[112:113], v[160:161], v[176:177] op_sel_hi:[0,1]
	v_pk_fma_f32 v[174:175], v[44:45], v[158:159], v[170:171] op_sel_hi:[1,0,1]
	s_waitcnt lgkmcnt(1)
	v_pk_mul_f32 v[170:171], v[164:165], v[178:179] op_sel_hi:[0,1]
	v_pk_fma_f32 v[176:177], v[46:47], v[158:159], v[112:113] op_sel_hi:[1,0,1]
	v_pk_mul_f32 v[112:113], v[164:165], v[180:181] op_sel_hi:[0,1]
	ds_read_b128 v[178:181], v137 offset:8960
	v_pk_mul_f32 v[44:45], v[168:169], v[212:213] op_sel_hi:[0,1]
	v_pk_mul_f32 v[46:47], v[168:169], v[214:215] op_sel_hi:[0,1]
	ds_read_b128 v[212:215], v137 offset:9472
	ds_read_b128 v[216:219], v137 offset:9984
	ds_read_b128 v[220:223], v137 offset:10112
	s_waitcnt lgkmcnt(4)
	v_add_f32_e32 v2, v210, v2
	ds_bpermute_b32 v110, v163, v2
	s_waitcnt lgkmcnt(4)
	v_pk_mul_f32 v[124:125], v[160:161], v[178:179] op_sel_hi:[0,1]
	v_pk_mul_f32 v[120:121], v[160:161], v[180:181] op_sel_hi:[0,1]
	v_pk_fma_f32 v[178:179], v[40:41], v[158:159], v[124:125] op_sel_hi:[1,0,1]
	s_waitcnt lgkmcnt(3)
	v_pk_mul_f32 v[124:125], v[164:165], v[212:213] op_sel_hi:[0,1]
	v_pk_fma_f32 v[180:181], v[42:43], v[158:159], v[120:121] op_sel_hi:[1,0,1]
	v_pk_mul_f32 v[120:121], v[164:165], v[214:215] op_sel_hi:[0,1]
	ds_read_b128 v[212:215], v137 offset:9088
	s_waitcnt lgkmcnt(3)
	v_pk_mul_f32 v[40:41], v[168:169], v[216:217] op_sel_hi:[0,1]
	v_pk_mul_f32 v[42:43], v[168:169], v[218:219] op_sel_hi:[0,1]
	ds_read_b128 v[216:219], v137 offset:9600
	s_waitcnt lgkmcnt(2)
	v_add_f32_e32 v2, v2, v110
	v_pk_fma_f32 v[150:151], v[154:155], v[162:163], v[104:105] op_sel_hi:[1,0,1]
	ds_read_b128 v[104:107], v137 offset:11904
	v_pk_fma_f32 v[172:173], v[176:177], v[162:163], v[112:113] op_sel_hi:[1,0,1]
	ds_read_b128 v[112:115], v137 offset:12032
	v_pk_fma_f32 v[126:127], v[180:181], v[162:163], v[120:121] op_sel_hi:[1,0,1]
	ds_read_b128 v[120:123], v137 offset:12160
	ds_bpermute_b32 v110, v165, v2
	s_waitcnt lgkmcnt(5)
	v_pk_mul_f32 v[116:117], v[160:161], v[212:213] op_sel_hi:[0,1]
	v_pk_mul_f32 v[108:109], v[160:161], v[214:215] op_sel_hi:[0,1]
	v_pk_fma_f32 v[182:183], v[36:37], v[158:159], v[116:117] op_sel_hi:[1,0,1]
	s_waitcnt lgkmcnt(4)
	v_pk_mul_f32 v[116:117], v[164:165], v[216:217] op_sel_hi:[0,1]
	v_pk_fma_f32 v[118:119], v[38:39], v[158:159], v[108:109] op_sel_hi:[1,0,1]
	v_pk_mul_f32 v[108:109], v[164:165], v[218:219] op_sel_hi:[0,1]
	v_pk_fma_f32 v[170:171], v[174:175], v[162:163], v[170:171] op_sel_hi:[1,0,1]
	v_pk_fma_f32 v[124:125], v[178:179], v[162:163], v[124:125] op_sel_hi:[1,0,1]
	v_pk_fma_f32 v[116:117], v[182:183], v[162:163], v[116:117] op_sel_hi:[1,0,1]
	v_pk_mul_f32 v[36:37], v[168:169], v[220:221] op_sel_hi:[0,1]
	v_pk_fma_f32 v[108:109], v[118:119], v[162:163], v[108:109] op_sel_hi:[1,0,1]
	v_pk_mul_f32 v[38:39], v[168:169], v[222:223] op_sel_hi:[0,1]
	v_pk_fma_f32 v[48:49], v[148:149], v[166:167], v[48:49] op_sel_hi:[1,0,1]
	v_pk_fma_f32 v[50:51], v[150:151], v[166:167], v[50:51] op_sel_hi:[1,0,1]
	v_pk_fma_f32 v[44:45], v[170:171], v[166:167], v[44:45] op_sel_hi:[1,0,1]
	v_pk_fma_f32 v[46:47], v[172:173], v[166:167], v[46:47] op_sel_hi:[1,0,1]
	v_pk_fma_f32 v[40:41], v[124:125], v[166:167], v[40:41] op_sel_hi:[1,0,1]
	v_pk_fma_f32 v[42:43], v[126:127], v[166:167], v[42:43] op_sel_hi:[1,0,1]
	v_pk_fma_f32 v[36:37], v[116:117], v[166:167], v[36:37] op_sel_hi:[1,0,1]
	v_pk_fma_f32 v[38:39], v[108:109], v[166:167], v[38:39] op_sel_hi:[1,0,1]
	global_store_dwordx4 v[140:141], v[48:51], off offset:-32
	global_store_dwordx4 v[140:141], v[44:47], off offset:96
	global_store_dwordx4 v[140:141], v[40:43], off offset:224
	global_store_dwordx4 v[140:141], v[36:39], off offset:352
	s_waitcnt vmcnt(8)
	s_and_saveexec_b64 s[16:17], vcc
	s_cbranch_execz .Lsmp_h0_743
	v_lshlrev_b32_e32 v111, 16, v209
	v_mul_f32_e32 v156, 0xbfb8aa3b, v111
	v_exp_f32_e32 v156, v156
	ds_read_b32 v158, v189
	s_waitcnt lgkmcnt(1)
	v_add_f32_e32 v2, v2, v110
	v_add_f32_e32 v156, 1.0, v156
	v_rcp_f32_e32 v156, v156
	s_waitcnt lgkmcnt(0)
	v_fmac_f32_e32 v2, s12, v158
	v_mul_f32_e32 v110, v156, v111
	v_mul_f32_e32 v2, v110, v2
	ds_write_b32 v189, v2 offset:12544

.Lsmp_h0_end:
	s_or_b64 exec, exec, s[16:17]
	s_add_i32 s13, s13, 4
	s_waitcnt lgkmcnt(0)
	s_mov_b64 s[14:15], 0x8000
	v_lshl_add_u64 v[140:141], v[140:141], 0, s[14:15]
	v_lshl_add_u64 v[144:145], v[144:145], 0, s[14:15]
	v_add_u32_e32 v185, 0x100, v185
	global_load_dwordx4 v[36:39], v[144:145], off offset:352
	global_load_dwordx4 v[40:43], v[144:145], off offset:224
	global_load_dwordx4 v[44:47], v[144:145], off offset:96
	global_load_dwordx4 v[48:51], v[144:145], off offset:-32
	s_lshl_b32 s14, s57, 5
	s_add_u32 s14, s60, s14
	s_addc_u32 s15, s61, 0
	s_nop 0
	s_load_dword s12, s[2:3], 0x4
	s_load_dword s14, s[14:15], 0x4
	v_and_b32_e32 v2, 7, v157
	v_cmp_eq_u32_e32 vcc, 1, v2
	v_add_u32_e32 v189, 0, v185
	s_waitcnt lgkmcnt(0)
	v_mov_b32_e32 v2, s14
	s_mov_b32 s14, 0x3fb8aa3b
	v_mul_f32_e32 v68, 0x3fb8aa3b, v2
	v_fma_f32 v69, v2, s14, -v68
	v_rndne_f32_e32 v70, v68
	v_fmac_f32_e32 v69, 0x32a5705f, v2
	v_sub_f32_e32 v68, v68, v70
	v_add_f32_e32 v68, v68, v69
	v_exp_f32_e32 v68, v68
	v_cvt_i32_f32_e32 v69, v70
	s_mov_b32 s14, 0xc2ce8ed0
	v_cmp_ngt_f32_e64 s[38:39], s14, v2
	s_mov_b32 s14, 0x42b17218
	v_ldexp_f32 v68, v68, v69
	v_cndmask_b32_e64 v68, 0, v68, s[38:39]
	v_cmp_nlt_f32_e64 s[38:39], s14, v2
	s_add_i32 s14, s13, 0
	v_mov_b32_e32 v72, s14
	v_cndmask_b32_e64 v116, v203, v68, s[38:39]
	ds_read2_b32 v[68:69], v72 offset1:8
	ds_read2st64_b32 v[70:71], v189 offset1:8
	ds_read_b128 v[104:107], v137 offset:10240
	ds_read_b128 v[112:115], v137 offset:10368
	ds_read_b128 v[120:123], v137 offset:10496
	ds_read_b128 v[108:111], v137 offset:10624
	s_waitcnt lgkmcnt(5)
	v_mul_f32_e64 v2, v68, -v116
	s_waitcnt lgkmcnt(4)
	v_mul_f32_e32 v156, v68, v70
	v_mul_f32_e64 v68, v69, -v116
	v_mul_f32_e32 v68, 0x3fb8aa3b, v68
	v_exp_f32_e32 v158, v68
	v_mul_f32_e32 v160, v69, v71
	ds_read_b128 v[100:103], v137 offset:10752
	ds_read_b128 v[96:99], v137 offset:10880
	ds_read_b128 v[92:95], v137 offset:11008
	ds_read_b128 v[88:91], v137 offset:11136
	ds_read2_b32 v[68:69], v72 offset0:16 offset1:24
	v_mul_f32_e32 v2, 0x3fb8aa3b, v2
	v_exp_f32_e32 v2, v2
	s_waitcnt lgkmcnt(0)
	v_mul_f32_e64 v70, v68, -v116
	v_mul_f32_e32 v70, 0x3fb8aa3b, v70
	v_exp_f32_e32 v162, v70
	ds_read2st64_b32 v[70:71], v189 offset0:16 offset1:24
	ds_read_b128 v[84:87], v137 offset:11264
	ds_read_b128 v[80:83], v137 offset:11392
	ds_read_b128 v[76:79], v137 offset:11520
	ds_read_b128 v[72:75], v137 offset:11648
	s_waitcnt lgkmcnt(4)
	v_mul_f32_e32 v164, v68, v70
	v_mul_f32_e64 v68, v69, -v116
	v_mul_f32_e32 v68, 0x3fb8aa3b, v68
	v_exp_f32_e32 v166, v68
	v_mul_f32_e32 v168, v69, v71
	ds_read_b128 v[68:71], v137 offset:11776
	ds_read_b128 v[148:151], v137 offset:8192
	ds_read_b128 v[170:173], v137 offset:8320
	ds_read_b128 v[124:127], v137 offset:8448
	ds_read_b128 v[116:119], v137 offset:8576
	ds_read_b128 v[152:155], v137 offset:8704
	ds_read_b128 v[174:177], v137 offset:9216
	s_waitcnt lgkmcnt(5)
	v_pk_mul_f32 v[148:149], v[156:157], v[148:149] op_sel_hi:[0,1]
	v_pk_fma_f32 v[12:13], v[12:13], v[2:3], v[148:149] op_sel_hi:[1,0,1]
	s_waitcnt lgkmcnt(4)
	v_pk_mul_f32 v[170:171], v[156:157], v[170:171] op_sel_hi:[0,1]
	v_fma_f32 v210, v12, v104, 0
	v_fmac_f32_e32 v210, v13, v105
	s_waitcnt lgkmcnt(1)
	v_pk_mul_f32 v[104:105], v[160:161], v[152:153] op_sel_hi:[0,1]
	v_pk_fma_f32 v[152:153], v[12:13], v[158:159], v[104:105] op_sel_hi:[1,0,1]
	v_pk_mul_f32 v[104:105], v[156:157], v[150:151] op_sel_hi:[0,1]
	v_pk_fma_f32 v[14:15], v[14:15], v[2:3], v[104:105] op_sel_hi:[1,0,1]
	v_pk_fma_f32 v[8:9], v[8:9], v[2:3], v[170:171] op_sel_hi:[1,0,1]
	v_fmac_f32_e32 v210, v14, v106
	v_fmac_f32_e32 v210, v15, v107
	v_fmac_f32_e32 v210, v8, v112
	v_fmac_f32_e32 v210, v9, v113
	v_pk_mul_f32 v[112:113], v[156:157], v[172:173] op_sel_hi:[0,1]
	v_pk_fma_f32 v[10:11], v[10:11], v[2:3], v[112:113] op_sel_hi:[1,0,1]
	v_pk_mul_f32 v[124:125], v[156:157], v[124:125] op_sel_hi:[0,1]
	v_fmac_f32_e32 v210, v10, v114
	v_fmac_f32_e32 v210, v11, v115
	v_pk_fma_f32 v[4:5], v[4:5], v[2:3], v[124:125] op_sel_hi:[1,0,1]
	ds_read_b128 v[178:181], v137 offset:9728
	ds_read_b128 v[212:215], v137 offset:9856
	v_fmac_f32_e32 v210, v4, v120
	v_fmac_f32_e32 v210, v5, v121
	v_pk_mul_f32 v[120:121], v[156:157], v[126:127] op_sel_hi:[0,1]
	v_pk_fma_f32 v[6:7], v[6:7], v[2:3], v[120:121] op_sel_hi:[1,0,1]
	v_pk_mul_f32 v[116:117], v[156:157], v[116:117] op_sel_hi:[0,1]
	v_fmac_f32_e32 v210, v6, v122
	v_fmac_f32_e32 v210, v7, v123
	v_pk_fma_f32 v[28:29], v[28:29], v[2:3], v[116:117] op_sel_hi:[1,0,1]
	v_pk_mul_f32 v[104:105], v[160:161], v[154:155] op_sel_hi:[0,1]
	v_fmac_f32_e32 v210, v28, v108
	s_waitcnt lgkmcnt(2)
	v_pk_mul_f32 v[12:13], v[164:165], v[174:175] op_sel_hi:[0,1]
	v_pk_fma_f32 v[154:155], v[14:15], v[158:159], v[104:105] op_sel_hi:[1,0,1]
	v_pk_mul_f32 v[104:105], v[164:165], v[176:177] op_sel_hi:[0,1]
	ds_read_b128 v[174:177], v137 offset:8832
	v_fmac_f32_e32 v210, v29, v109
	v_pk_mul_f32 v[108:109], v[156:157], v[118:119] op_sel_hi:[0,1]
	v_pk_fma_f32 v[148:149], v[152:153], v[162:163], v[12:13] op_sel_hi:[1,0,1]
	s_waitcnt lgkmcnt(2)
	v_pk_mul_f32 v[12:13], v[168:169], v[178:179] op_sel_hi:[0,1]
	v_pk_mul_f32 v[14:15], v[168:169], v[180:181] op_sel_hi:[0,1]
	ds_read_b128 v[178:181], v137 offset:9344
	v_pk_fma_f32 v[30:31], v[30:31], v[2:3], v[108:109] op_sel_hi:[1,0,1]
	s_waitcnt lgkmcnt(1)
	v_pk_mul_f32 v[170:171], v[160:161], v[174:175] op_sel_hi:[0,1]
	v_fmac_f32_e32 v210, v30, v110
	v_fmac_f32_e32 v210, v31, v111
	ds_bpermute_b32 v2, v161, v210
	v_pk_mul_f32 v[112:113], v[160:161], v[176:177] op_sel_hi:[0,1]
	v_pk_fma_f32 v[174:175], v[8:9], v[158:159], v[170:171] op_sel_hi:[1,0,1]
	s_waitcnt lgkmcnt(1)
	v_pk_mul_f32 v[170:171], v[164:165], v[178:179] op_sel_hi:[0,1]
	v_pk_fma_f32 v[176:177], v[10:11], v[158:159], v[112:113] op_sel_hi:[1,0,1]
	v_pk_mul_f32 v[112:113], v[164:165], v[180:181] op_sel_hi:[0,1]
	ds_read_b128 v[178:181], v137 offset:8960
	v_pk_mul_f32 v[8:9], v[168:169], v[212:213] op_sel_hi:[0,1]
	v_pk_mul_f32 v[10:11], v[168:169], v[214:215] op_sel_hi:[0,1]
	ds_read_b128 v[212:215], v137 offset:9472
	ds_read_b128 v[216:219], v137 offset:9984
	ds_read_b128 v[220:223], v137 offset:10112
	s_waitcnt lgkmcnt(4)
	v_add_f32_e32 v2, v210, v2
	ds_bpermute_b32 v110, v163, v2
	s_waitcnt lgkmcnt(4)
	v_pk_mul_f32 v[124:125], v[160:161], v[178:179] op_sel_hi:[0,1]
	v_pk_mul_f32 v[120:121], v[160:161], v[180:181] op_sel_hi:[0,1]
	v_pk_fma_f32 v[178:179], v[4:5], v[158:159], v[124:125] op_sel_hi:[1,0,1]
	s_waitcnt lgkmcnt(3)
	v_pk_mul_f32 v[124:125], v[164:165], v[212:213] op_sel_hi:[0,1]
	v_pk_fma_f32 v[180:181], v[6:7], v[158:159], v[120:121] op_sel_hi:[1,0,1]
	v_pk_mul_f32 v[120:121], v[164:165], v[214:215] op_sel_hi:[0,1]
	ds_read_b128 v[212:215], v137 offset:9088
	s_waitcnt lgkmcnt(3)
	v_pk_mul_f32 v[4:5], v[168:169], v[216:217] op_sel_hi:[0,1]
	v_pk_mul_f32 v[6:7], v[168:169], v[218:219] op_sel_hi:[0,1]
	ds_read_b128 v[216:219], v137 offset:9600
	s_waitcnt lgkmcnt(2)
	v_add_f32_e32 v2, v2, v110
	v_pk_fma_f32 v[150:151], v[154:155], v[162:163], v[104:105] op_sel_hi:[1,0,1]
	ds_read_b128 v[104:107], v137 offset:11904
	v_pk_fma_f32 v[172:173], v[176:177], v[162:163], v[112:113] op_sel_hi:[1,0,1]
	ds_read_b128 v[112:115], v137 offset:12032
	v_pk_fma_f32 v[126:127], v[180:181], v[162:163], v[120:121] op_sel_hi:[1,0,1]
	ds_read_b128 v[120:123], v137 offset:12160
	ds_bpermute_b32 v110, v165, v2
	s_waitcnt lgkmcnt(5)
	v_pk_mul_f32 v[116:117], v[160:161], v[212:213] op_sel_hi:[0,1]
	v_pk_mul_f32 v[108:109], v[160:161], v[214:215] op_sel_hi:[0,1]
	v_pk_fma_f32 v[182:183], v[28:29], v[158:159], v[116:117] op_sel_hi:[1,0,1]
	s_waitcnt lgkmcnt(4)
	v_pk_mul_f32 v[116:117], v[164:165], v[216:217] op_sel_hi:[0,1]
	v_pk_fma_f32 v[118:119], v[30:31], v[158:159], v[108:109] op_sel_hi:[1,0,1]
	v_pk_mul_f32 v[108:109], v[164:165], v[218:219] op_sel_hi:[0,1]
	v_pk_fma_f32 v[170:171], v[174:175], v[162:163], v[170:171] op_sel_hi:[1,0,1]
	v_pk_fma_f32 v[124:125], v[178:179], v[162:163], v[124:125] op_sel_hi:[1,0,1]
	v_pk_fma_f32 v[116:117], v[182:183], v[162:163], v[116:117] op_sel_hi:[1,0,1]
	v_pk_mul_f32 v[28:29], v[168:169], v[220:221] op_sel_hi:[0,1]
	v_pk_fma_f32 v[108:109], v[118:119], v[162:163], v[108:109] op_sel_hi:[1,0,1]
	v_pk_mul_f32 v[30:31], v[168:169], v[222:223] op_sel_hi:[0,1]
	v_pk_fma_f32 v[12:13], v[148:149], v[166:167], v[12:13] op_sel_hi:[1,0,1]
	v_pk_fma_f32 v[14:15], v[150:151], v[166:167], v[14:15] op_sel_hi:[1,0,1]
	v_pk_fma_f32 v[8:9], v[170:171], v[166:167], v[8:9] op_sel_hi:[1,0,1]
	v_pk_fma_f32 v[10:11], v[172:173], v[166:167], v[10:11] op_sel_hi:[1,0,1]
	v_pk_fma_f32 v[4:5], v[124:125], v[166:167], v[4:5] op_sel_hi:[1,0,1]
	v_pk_fma_f32 v[6:7], v[126:127], v[166:167], v[6:7] op_sel_hi:[1,0,1]
	v_pk_fma_f32 v[28:29], v[116:117], v[166:167], v[28:29] op_sel_hi:[1,0,1]
	v_pk_fma_f32 v[30:31], v[108:109], v[166:167], v[30:31] op_sel_hi:[1,0,1]
	global_store_dwordx4 v[140:141], v[12:15], off offset:-32
	global_store_dwordx4 v[140:141], v[8:11], off offset:96
	global_store_dwordx4 v[140:141], v[4:7], off offset:224
	global_store_dwordx4 v[140:141], v[28:31], off offset:352
	s_and_saveexec_b64 s[16:17], vcc
	s_cbranch_execz .Lsmp_h1_743
	v_lshlrev_b32_e32 v111, 16, v209
	v_mul_f32_e32 v156, 0xbfb8aa3b, v111
	v_exp_f32_e32 v156, v156
	ds_read_b32 v158, v189
	s_waitcnt lgkmcnt(1)
	v_add_f32_e32 v2, v2, v110
	v_add_f32_e32 v156, 1.0, v156
	v_rcp_f32_e32 v156, v156
	s_waitcnt lgkmcnt(0)
	v_fmac_f32_e32 v2, s12, v158
	v_mul_f32_e32 v110, v156, v111
	v_mul_f32_e32 v2, v110, v2
	ds_write_b32 v189, v2 offset:12544

.Lsmp_h1_end:
	s_or_b64 exec, exec, s[16:17]
	s_add_i32 s13, s13, 4
	s_waitcnt lgkmcnt(0)
	s_mov_b64 s[14:15], 0x8000
	v_lshl_add_u64 v[140:141], v[140:141], 0, s[14:15]
	v_lshl_add_u64 v[144:145], v[144:145], 0, s[14:15]
	v_add_u32_e32 v185, 0x100, v185
	global_load_dwordx4 v[28:31], v[144:145], off offset:352
	global_load_dwordx4 v[4:7], v[144:145], off offset:224
	global_load_dwordx4 v[8:11], v[144:145], off offset:96
	global_load_dwordx4 v[12:15], v[144:145], off offset:-32
	s_lshl_b32 s14, s57, 5
	s_add_u32 s14, s60, s14
	s_addc_u32 s15, s61, 0
	s_nop 0
	s_load_dword s12, s[2:3], 0x8
	s_load_dword s14, s[14:15], 0x8
	v_and_b32_e32 v2, 7, v157
	v_cmp_eq_u32_e32 vcc, 2, v2
	v_add_u32_e32 v189, 0, v185
	s_waitcnt lgkmcnt(0)
	v_mov_b32_e32 v2, s14
	s_mov_b32 s14, 0x3fb8aa3b
	v_mul_f32_e32 v68, 0x3fb8aa3b, v2
	v_fma_f32 v69, v2, s14, -v68
	v_rndne_f32_e32 v70, v68
	v_fmac_f32_e32 v69, 0x32a5705f, v2
	v_sub_f32_e32 v68, v68, v70
	v_add_f32_e32 v68, v68, v69
	v_exp_f32_e32 v68, v68
	v_cvt_i32_f32_e32 v69, v70
	s_mov_b32 s14, 0xc2ce8ed0
	v_cmp_ngt_f32_e64 s[38:39], s14, v2
	s_mov_b32 s14, 0x42b17218
	v_ldexp_f32 v68, v68, v69
	v_cndmask_b32_e64 v68, 0, v68, s[38:39]
	v_cmp_nlt_f32_e64 s[38:39], s14, v2
	s_add_i32 s14, s13, 0
	v_mov_b32_e32 v72, s14
	v_cndmask_b32_e64 v116, v203, v68, s[38:39]
	ds_read2_b32 v[68:69], v72 offset1:8
	ds_read2st64_b32 v[70:71], v189 offset1:8
	ds_read_b128 v[104:107], v137 offset:10240
	ds_read_b128 v[112:115], v137 offset:10368
	ds_read_b128 v[120:123], v137 offset:10496
	ds_read_b128 v[108:111], v137 offset:10624
	s_waitcnt lgkmcnt(5)
	v_mul_f32_e64 v2, v68, -v116
	s_waitcnt lgkmcnt(4)
	v_mul_f32_e32 v156, v68, v70
	v_mul_f32_e64 v68, v69, -v116
	v_mul_f32_e32 v68, 0x3fb8aa3b, v68
	v_exp_f32_e32 v158, v68
	v_mul_f32_e32 v160, v69, v71
	ds_read_b128 v[100:103], v137 offset:10752
	ds_read_b128 v[96:99], v137 offset:10880
	ds_read_b128 v[92:95], v137 offset:11008
	ds_read_b128 v[88:91], v137 offset:11136
	ds_read2_b32 v[68:69], v72 offset0:16 offset1:24
	v_mul_f32_e32 v2, 0x3fb8aa3b, v2
	v_exp_f32_e32 v2, v2
	s_waitcnt lgkmcnt(0)
	v_mul_f32_e64 v70, v68, -v116
	v_mul_f32_e32 v70, 0x3fb8aa3b, v70
	v_exp_f32_e32 v162, v70
	ds_read2st64_b32 v[70:71], v189 offset0:16 offset1:24
	ds_read_b128 v[84:87], v137 offset:11264
	ds_read_b128 v[80:83], v137 offset:11392
	ds_read_b128 v[76:79], v137 offset:11520
	ds_read_b128 v[72:75], v137 offset:11648
	s_waitcnt lgkmcnt(4)
	v_mul_f32_e32 v164, v68, v70
	v_mul_f32_e64 v68, v69, -v116
	v_mul_f32_e32 v68, 0x3fb8aa3b, v68
	v_exp_f32_e32 v166, v68
	v_mul_f32_e32 v168, v69, v71
	ds_read_b128 v[68:71], v137 offset:11776
	ds_read_b128 v[148:151], v137 offset:8192
	ds_read_b128 v[170:173], v137 offset:8320
	ds_read_b128 v[124:127], v137 offset:8448
	ds_read_b128 v[116:119], v137 offset:8576
	ds_read_b128 v[152:155], v137 offset:8704
	ds_read_b128 v[174:177], v137 offset:9216
	s_waitcnt lgkmcnt(5)
	v_pk_mul_f32 v[148:149], v[156:157], v[148:149] op_sel_hi:[0,1]
	v_pk_fma_f32 v[16:17], v[16:17], v[2:3], v[148:149] op_sel_hi:[1,0,1]
	s_waitcnt lgkmcnt(4)
	v_pk_mul_f32 v[170:171], v[156:157], v[170:171] op_sel_hi:[0,1]
	v_fma_f32 v210, v16, v104, 0
	v_fmac_f32_e32 v210, v17, v105
	s_waitcnt lgkmcnt(1)
	v_pk_mul_f32 v[104:105], v[160:161], v[152:153] op_sel_hi:[0,1]
	v_pk_fma_f32 v[152:153], v[16:17], v[158:159], v[104:105] op_sel_hi:[1,0,1]
	v_pk_mul_f32 v[104:105], v[156:157], v[150:151] op_sel_hi:[0,1]
	v_pk_fma_f32 v[18:19], v[18:19], v[2:3], v[104:105] op_sel_hi:[1,0,1]
	v_pk_fma_f32 v[32:33], v[32:33], v[2:3], v[170:171] op_sel_hi:[1,0,1]
	v_fmac_f32_e32 v210, v18, v106
	v_fmac_f32_e32 v210, v19, v107
	v_fmac_f32_e32 v210, v32, v112
	v_fmac_f32_e32 v210, v33, v113
	v_pk_mul_f32 v[112:113], v[156:157], v[172:173] op_sel_hi:[0,1]
	v_pk_fma_f32 v[34:35], v[34:35], v[2:3], v[112:113] op_sel_hi:[1,0,1]
	v_pk_mul_f32 v[124:125], v[156:157], v[124:125] op_sel_hi:[0,1]
	v_fmac_f32_e32 v210, v34, v114
	v_fmac_f32_e32 v210, v35, v115
	v_pk_fma_f32 v[24:25], v[24:25], v[2:3], v[124:125] op_sel_hi:[1,0,1]
	ds_read_b128 v[178:181], v137 offset:9728
	ds_read_b128 v[212:215], v137 offset:9856
	v_fmac_f32_e32 v210, v24, v120
	v_fmac_f32_e32 v210, v25, v121
	v_pk_mul_f32 v[120:121], v[156:157], v[126:127] op_sel_hi:[0,1]
	v_pk_fma_f32 v[26:27], v[26:27], v[2:3], v[120:121] op_sel_hi:[1,0,1]
	v_pk_mul_f32 v[116:117], v[156:157], v[116:117] op_sel_hi:[0,1]
	v_fmac_f32_e32 v210, v26, v122
	v_fmac_f32_e32 v210, v27, v123
	v_pk_fma_f32 v[20:21], v[20:21], v[2:3], v[116:117] op_sel_hi:[1,0,1]
	v_pk_mul_f32 v[104:105], v[160:161], v[154:155] op_sel_hi:[0,1]
	v_fmac_f32_e32 v210, v20, v108
	s_waitcnt lgkmcnt(2)
	v_pk_mul_f32 v[16:17], v[164:165], v[174:175] op_sel_hi:[0,1]
	v_pk_fma_f32 v[154:155], v[18:19], v[158:159], v[104:105] op_sel_hi:[1,0,1]
	v_pk_mul_f32 v[104:105], v[164:165], v[176:177] op_sel_hi:[0,1]
	ds_read_b128 v[174:177], v137 offset:8832
	v_fmac_f32_e32 v210, v21, v109
	v_pk_mul_f32 v[108:109], v[156:157], v[118:119] op_sel_hi:[0,1]
	v_pk_fma_f32 v[148:149], v[152:153], v[162:163], v[16:17] op_sel_hi:[1,0,1]
	s_waitcnt lgkmcnt(2)
	v_pk_mul_f32 v[16:17], v[168:169], v[178:179] op_sel_hi:[0,1]
	v_pk_mul_f32 v[18:19], v[168:169], v[180:181] op_sel_hi:[0,1]
	ds_read_b128 v[178:181], v137 offset:9344
	v_pk_fma_f32 v[22:23], v[22:23], v[2:3], v[108:109] op_sel_hi:[1,0,1]
	s_waitcnt lgkmcnt(1)
	v_pk_mul_f32 v[170:171], v[160:161], v[174:175] op_sel_hi:[0,1]
	v_fmac_f32_e32 v210, v22, v110
	v_fmac_f32_e32 v210, v23, v111
	ds_bpermute_b32 v2, v161, v210
	v_pk_mul_f32 v[112:113], v[160:161], v[176:177] op_sel_hi:[0,1]
	v_pk_fma_f32 v[174:175], v[32:33], v[158:159], v[170:171] op_sel_hi:[1,0,1]
	s_waitcnt lgkmcnt(1)
	v_pk_mul_f32 v[170:171], v[164:165], v[178:179] op_sel_hi:[0,1]
	v_pk_fma_f32 v[176:177], v[34:35], v[158:159], v[112:113] op_sel_hi:[1,0,1]
	v_pk_mul_f32 v[112:113], v[164:165], v[180:181] op_sel_hi:[0,1]
	ds_read_b128 v[178:181], v137 offset:8960
	v_pk_mul_f32 v[32:33], v[168:169], v[212:213] op_sel_hi:[0,1]
	v_pk_mul_f32 v[34:35], v[168:169], v[214:215] op_sel_hi:[0,1]
	ds_read_b128 v[212:215], v137 offset:9472
	ds_read_b128 v[216:219], v137 offset:9984
	ds_read_b128 v[220:223], v137 offset:10112
	s_waitcnt lgkmcnt(4)
	v_add_f32_e32 v2, v210, v2
	ds_bpermute_b32 v110, v163, v2
	s_waitcnt lgkmcnt(4)
	v_pk_mul_f32 v[124:125], v[160:161], v[178:179] op_sel_hi:[0,1]
	v_pk_mul_f32 v[120:121], v[160:161], v[180:181] op_sel_hi:[0,1]
	v_pk_fma_f32 v[178:179], v[24:25], v[158:159], v[124:125] op_sel_hi:[1,0,1]
	s_waitcnt lgkmcnt(3)
	v_pk_mul_f32 v[124:125], v[164:165], v[212:213] op_sel_hi:[0,1]
	v_pk_fma_f32 v[180:181], v[26:27], v[158:159], v[120:121] op_sel_hi:[1,0,1]
	v_pk_mul_f32 v[120:121], v[164:165], v[214:215] op_sel_hi:[0,1]
	ds_read_b128 v[212:215], v137 offset:9088
	s_waitcnt lgkmcnt(3)
	v_pk_mul_f32 v[24:25], v[168:169], v[216:217] op_sel_hi:[0,1]
	v_pk_mul_f32 v[26:27], v[168:169], v[218:219] op_sel_hi:[0,1]
	ds_read_b128 v[216:219], v137 offset:9600
	s_waitcnt lgkmcnt(2)
	v_add_f32_e32 v2, v2, v110
	v_pk_fma_f32 v[150:151], v[154:155], v[162:163], v[104:105] op_sel_hi:[1,0,1]
	ds_read_b128 v[104:107], v137 offset:11904
	v_pk_fma_f32 v[172:173], v[176:177], v[162:163], v[112:113] op_sel_hi:[1,0,1]
	ds_read_b128 v[112:115], v137 offset:12032
	v_pk_fma_f32 v[126:127], v[180:181], v[162:163], v[120:121] op_sel_hi:[1,0,1]
	ds_read_b128 v[120:123], v137 offset:12160
	ds_bpermute_b32 v110, v165, v2
	s_waitcnt lgkmcnt(5)
	v_pk_mul_f32 v[116:117], v[160:161], v[212:213] op_sel_hi:[0,1]
	v_pk_mul_f32 v[108:109], v[160:161], v[214:215] op_sel_hi:[0,1]
	v_pk_fma_f32 v[182:183], v[20:21], v[158:159], v[116:117] op_sel_hi:[1,0,1]
	s_waitcnt lgkmcnt(4)
	v_pk_mul_f32 v[116:117], v[164:165], v[216:217] op_sel_hi:[0,1]
	v_pk_fma_f32 v[118:119], v[22:23], v[158:159], v[108:109] op_sel_hi:[1,0,1]
	v_pk_mul_f32 v[108:109], v[164:165], v[218:219] op_sel_hi:[0,1]
	v_pk_fma_f32 v[170:171], v[174:175], v[162:163], v[170:171] op_sel_hi:[1,0,1]
	v_pk_fma_f32 v[124:125], v[178:179], v[162:163], v[124:125] op_sel_hi:[1,0,1]
	v_pk_fma_f32 v[116:117], v[182:183], v[162:163], v[116:117] op_sel_hi:[1,0,1]
	v_pk_mul_f32 v[20:21], v[168:169], v[220:221] op_sel_hi:[0,1]
	v_pk_fma_f32 v[108:109], v[118:119], v[162:163], v[108:109] op_sel_hi:[1,0,1]
	v_pk_mul_f32 v[22:23], v[168:169], v[222:223] op_sel_hi:[0,1]
	v_pk_fma_f32 v[16:17], v[148:149], v[166:167], v[16:17] op_sel_hi:[1,0,1]
	v_pk_fma_f32 v[18:19], v[150:151], v[166:167], v[18:19] op_sel_hi:[1,0,1]
	v_pk_fma_f32 v[32:33], v[170:171], v[166:167], v[32:33] op_sel_hi:[1,0,1]
	v_pk_fma_f32 v[34:35], v[172:173], v[166:167], v[34:35] op_sel_hi:[1,0,1]
	v_pk_fma_f32 v[24:25], v[124:125], v[166:167], v[24:25] op_sel_hi:[1,0,1]
	v_pk_fma_f32 v[26:27], v[126:127], v[166:167], v[26:27] op_sel_hi:[1,0,1]
	v_pk_fma_f32 v[20:21], v[116:117], v[166:167], v[20:21] op_sel_hi:[1,0,1]
	v_pk_fma_f32 v[22:23], v[108:109], v[166:167], v[22:23] op_sel_hi:[1,0,1]
	global_store_dwordx4 v[140:141], v[16:19], off offset:-32
	global_store_dwordx4 v[140:141], v[32:35], off offset:96
	global_store_dwordx4 v[140:141], v[24:27], off offset:224
	global_store_dwordx4 v[140:141], v[20:23], off offset:352
	s_and_saveexec_b64 s[16:17], vcc
	s_cbranch_execz .Lsmp_h2_743
	v_lshlrev_b32_e32 v111, 16, v209
	v_mul_f32_e32 v156, 0xbfb8aa3b, v111
	v_exp_f32_e32 v156, v156
	ds_read_b32 v158, v189
	s_waitcnt lgkmcnt(1)
	v_add_f32_e32 v2, v2, v110
	v_add_f32_e32 v156, 1.0, v156
	v_rcp_f32_e32 v156, v156
	s_waitcnt lgkmcnt(0)
	v_fmac_f32_e32 v2, s12, v158
	v_mul_f32_e32 v110, v156, v111
	v_mul_f32_e32 v2, v110, v2
	ds_write_b32 v189, v2 offset:12544

.Lsmp_h2_end:
	s_or_b64 exec, exec, s[16:17]
	s_add_i32 s13, s13, 4
	s_waitcnt lgkmcnt(0)
	s_mov_b64 s[14:15], 0x8000
	v_lshl_add_u64 v[140:141], v[140:141], 0, s[14:15]
	v_lshl_add_u64 v[144:145], v[144:145], 0, s[14:15]
	v_add_u32_e32 v185, 0x100, v185
	global_load_dwordx4 v[20:23], v[144:145], off offset:352
	global_load_dwordx4 v[24:27], v[144:145], off offset:224
	global_load_dwordx4 v[32:35], v[144:145], off offset:96
	global_load_dwordx4 v[16:19], v[144:145], off offset:-32
	s_lshl_b32 s14, s57, 5
	s_add_u32 s14, s60, s14
	s_addc_u32 s15, s61, 0
	s_nop 0
	s_load_dword s12, s[2:3], 0xc
	s_load_dword s14, s[14:15], 0xc
	v_and_b32_e32 v2, 7, v157
	v_cmp_eq_u32_e32 vcc, 3, v2
	v_add_u32_e32 v189, 0, v185
	s_waitcnt lgkmcnt(0)
	v_mov_b32_e32 v2, s14
	s_mov_b32 s14, 0x3fb8aa3b
	s_waitcnt vmcnt(24)
	v_mul_f32_e32 v68, 0x3fb8aa3b, v2
	v_fma_f32 v69, v2, s14, -v68
	v_rndne_f32_e32 v70, v68
	v_fmac_f32_e32 v69, 0x32a5705f, v2
	v_sub_f32_e32 v68, v68, v70
	v_add_f32_e32 v68, v68, v69
	v_exp_f32_e32 v68, v68
	v_cvt_i32_f32_e32 v69, v70
	s_mov_b32 s14, 0xc2ce8ed0
	v_cmp_ngt_f32_e64 s[38:39], s14, v2
	s_mov_b32 s14, 0x42b17218
	v_ldexp_f32 v68, v68, v69
	v_cndmask_b32_e64 v68, 0, v68, s[38:39]
	v_cmp_nlt_f32_e64 s[38:39], s14, v2
	s_add_i32 s14, s13, 0
	v_mov_b32_e32 v72, s14
	v_cndmask_b32_e64 v116, v203, v68, s[38:39]
	ds_read2_b32 v[68:69], v72 offset1:8
	ds_read2st64_b32 v[70:71], v189 offset1:8
	ds_read_b128 v[104:107], v137 offset:10240
	ds_read_b128 v[112:115], v137 offset:10368
	ds_read_b128 v[120:123], v137 offset:10496
	ds_read_b128 v[108:111], v137 offset:10624
	s_waitcnt lgkmcnt(5)
	v_mul_f32_e64 v2, v68, -v116
	s_waitcnt lgkmcnt(4)
	v_mul_f32_e32 v156, v68, v70
	v_mul_f32_e64 v68, v69, -v116
	v_mul_f32_e32 v68, 0x3fb8aa3b, v68
	v_exp_f32_e32 v158, v68
	v_mul_f32_e32 v160, v69, v71
	ds_read_b128 v[100:103], v137 offset:10752
	ds_read_b128 v[96:99], v137 offset:10880
	ds_read_b128 v[92:95], v137 offset:11008
	ds_read_b128 v[88:91], v137 offset:11136
	ds_read2_b32 v[68:69], v72 offset0:16 offset1:24
	v_mul_f32_e32 v2, 0x3fb8aa3b, v2
	v_exp_f32_e32 v2, v2
	s_waitcnt lgkmcnt(0)
	v_mul_f32_e64 v70, v68, -v116
	v_mul_f32_e32 v70, 0x3fb8aa3b, v70
	v_exp_f32_e32 v162, v70
	ds_read2st64_b32 v[70:71], v189 offset0:16 offset1:24
	ds_read_b128 v[84:87], v137 offset:11264
	ds_read_b128 v[80:83], v137 offset:11392
	ds_read_b128 v[76:79], v137 offset:11520
	ds_read_b128 v[72:75], v137 offset:11648
	s_waitcnt lgkmcnt(4)
	v_mul_f32_e32 v164, v68, v70
	v_mul_f32_e64 v68, v69, -v116
	v_mul_f32_e32 v68, 0x3fb8aa3b, v68
	v_exp_f32_e32 v166, v68
	v_mul_f32_e32 v168, v69, v71
	ds_read_b128 v[68:71], v137 offset:11776
	ds_read_b128 v[148:151], v137 offset:8192
	ds_read_b128 v[170:173], v137 offset:8320
	ds_read_b128 v[124:127], v137 offset:8448
	ds_read_b128 v[116:119], v137 offset:8576
	ds_read_b128 v[152:155], v137 offset:8704
	ds_read_b128 v[174:177], v137 offset:9216
	s_waitcnt lgkmcnt(5)
	v_pk_mul_f32 v[148:149], v[156:157], v[148:149] op_sel_hi:[0,1]
	v_pk_fma_f32 v[64:65], v[64:65], v[2:3], v[148:149] op_sel_hi:[1,0,1]
	s_waitcnt lgkmcnt(4)
	v_pk_mul_f32 v[170:171], v[156:157], v[170:171] op_sel_hi:[0,1]
	v_fma_f32 v210, v64, v104, 0
	v_fmac_f32_e32 v210, v65, v105
	s_waitcnt lgkmcnt(1)
	v_pk_mul_f32 v[104:105], v[160:161], v[152:153] op_sel_hi:[0,1]
	v_pk_fma_f32 v[152:153], v[64:65], v[158:159], v[104:105] op_sel_hi:[1,0,1]
	v_pk_mul_f32 v[104:105], v[156:157], v[150:151] op_sel_hi:[0,1]
	v_pk_fma_f32 v[66:67], v[66:67], v[2:3], v[104:105] op_sel_hi:[1,0,1]
	v_pk_fma_f32 v[60:61], v[60:61], v[2:3], v[170:171] op_sel_hi:[1,0,1]
	v_fmac_f32_e32 v210, v66, v106
	v_fmac_f32_e32 v210, v67, v107
	v_fmac_f32_e32 v210, v60, v112
	v_fmac_f32_e32 v210, v61, v113
	v_pk_mul_f32 v[112:113], v[156:157], v[172:173] op_sel_hi:[0,1]
	v_pk_fma_f32 v[62:63], v[62:63], v[2:3], v[112:113] op_sel_hi:[1,0,1]
	v_pk_mul_f32 v[124:125], v[156:157], v[124:125] op_sel_hi:[0,1]
	v_fmac_f32_e32 v210, v62, v114
	v_fmac_f32_e32 v210, v63, v115
	v_pk_fma_f32 v[56:57], v[56:57], v[2:3], v[124:125] op_sel_hi:[1,0,1]
	ds_read_b128 v[178:181], v137 offset:9728
	ds_read_b128 v[212:215], v137 offset:9856
	v_fmac_f32_e32 v210, v56, v120
	v_fmac_f32_e32 v210, v57, v121
	v_pk_mul_f32 v[120:121], v[156:157], v[126:127] op_sel_hi:[0,1]
	v_pk_fma_f32 v[58:59], v[58:59], v[2:3], v[120:121] op_sel_hi:[1,0,1]
	v_pk_mul_f32 v[116:117], v[156:157], v[116:117] op_sel_hi:[0,1]
	v_fmac_f32_e32 v210, v58, v122
	v_fmac_f32_e32 v210, v59, v123
	v_pk_fma_f32 v[52:53], v[52:53], v[2:3], v[116:117] op_sel_hi:[1,0,1]
	v_pk_mul_f32 v[104:105], v[160:161], v[154:155] op_sel_hi:[0,1]
	v_fmac_f32_e32 v210, v52, v108
	s_waitcnt lgkmcnt(2)
	v_pk_mul_f32 v[64:65], v[164:165], v[174:175] op_sel_hi:[0,1]
	v_pk_fma_f32 v[154:155], v[66:67], v[158:159], v[104:105] op_sel_hi:[1,0,1]
	v_pk_mul_f32 v[104:105], v[164:165], v[176:177] op_sel_hi:[0,1]
	ds_read_b128 v[174:177], v137 offset:8832
	v_fmac_f32_e32 v210, v53, v109
	v_pk_mul_f32 v[108:109], v[156:157], v[118:119] op_sel_hi:[0,1]
	v_pk_fma_f32 v[148:149], v[152:153], v[162:163], v[64:65] op_sel_hi:[1,0,1]
	s_waitcnt lgkmcnt(2)
	v_pk_mul_f32 v[64:65], v[168:169], v[178:179] op_sel_hi:[0,1]
	v_pk_mul_f32 v[66:67], v[168:169], v[180:181] op_sel_hi:[0,1]
	ds_read_b128 v[178:181], v137 offset:9344
	v_pk_fma_f32 v[54:55], v[54:55], v[2:3], v[108:109] op_sel_hi:[1,0,1]
	s_waitcnt lgkmcnt(1)
	v_pk_mul_f32 v[170:171], v[160:161], v[174:175] op_sel_hi:[0,1]
	v_fmac_f32_e32 v210, v54, v110
	v_fmac_f32_e32 v210, v55, v111
	ds_bpermute_b32 v2, v161, v210
	v_pk_mul_f32 v[112:113], v[160:161], v[176:177] op_sel_hi:[0,1]
	v_pk_fma_f32 v[174:175], v[60:61], v[158:159], v[170:171] op_sel_hi:[1,0,1]
	s_waitcnt lgkmcnt(1)
	v_pk_mul_f32 v[170:171], v[164:165], v[178:179] op_sel_hi:[0,1]
	v_pk_fma_f32 v[176:177], v[62:63], v[158:159], v[112:113] op_sel_hi:[1,0,1]
	v_pk_mul_f32 v[112:113], v[164:165], v[180:181] op_sel_hi:[0,1]
	ds_read_b128 v[178:181], v137 offset:8960
	v_pk_mul_f32 v[60:61], v[168:169], v[212:213] op_sel_hi:[0,1]
	v_pk_mul_f32 v[62:63], v[168:169], v[214:215] op_sel_hi:[0,1]
	ds_read_b128 v[212:215], v137 offset:9472
	ds_read_b128 v[216:219], v137 offset:9984
	ds_read_b128 v[220:223], v137 offset:10112
	s_waitcnt lgkmcnt(4)
	v_add_f32_e32 v2, v210, v2
	ds_bpermute_b32 v110, v163, v2
	s_waitcnt lgkmcnt(4)
	v_pk_mul_f32 v[124:125], v[160:161], v[178:179] op_sel_hi:[0,1]
	v_pk_mul_f32 v[120:121], v[160:161], v[180:181] op_sel_hi:[0,1]
	v_pk_fma_f32 v[178:179], v[56:57], v[158:159], v[124:125] op_sel_hi:[1,0,1]
	s_waitcnt lgkmcnt(3)
	v_pk_mul_f32 v[124:125], v[164:165], v[212:213] op_sel_hi:[0,1]
	v_pk_fma_f32 v[180:181], v[58:59], v[158:159], v[120:121] op_sel_hi:[1,0,1]
	v_pk_mul_f32 v[120:121], v[164:165], v[214:215] op_sel_hi:[0,1]
	ds_read_b128 v[212:215], v137 offset:9088
	s_waitcnt lgkmcnt(3)
	v_pk_mul_f32 v[56:57], v[168:169], v[216:217] op_sel_hi:[0,1]
	v_pk_mul_f32 v[58:59], v[168:169], v[218:219] op_sel_hi:[0,1]
	ds_read_b128 v[216:219], v137 offset:9600
	s_waitcnt lgkmcnt(2)
	v_add_f32_e32 v2, v2, v110
	v_pk_fma_f32 v[150:151], v[154:155], v[162:163], v[104:105] op_sel_hi:[1,0,1]
	ds_read_b128 v[104:107], v137 offset:11904
	v_pk_fma_f32 v[172:173], v[176:177], v[162:163], v[112:113] op_sel_hi:[1,0,1]
	ds_read_b128 v[112:115], v137 offset:12032
	v_pk_fma_f32 v[126:127], v[180:181], v[162:163], v[120:121] op_sel_hi:[1,0,1]
	ds_read_b128 v[120:123], v137 offset:12160
	ds_bpermute_b32 v110, v165, v2
	s_waitcnt lgkmcnt(5)
	v_pk_mul_f32 v[116:117], v[160:161], v[212:213] op_sel_hi:[0,1]
	v_pk_mul_f32 v[108:109], v[160:161], v[214:215] op_sel_hi:[0,1]
	v_pk_fma_f32 v[182:183], v[52:53], v[158:159], v[116:117] op_sel_hi:[1,0,1]
	s_waitcnt lgkmcnt(4)
	v_pk_mul_f32 v[116:117], v[164:165], v[216:217] op_sel_hi:[0,1]
	v_pk_fma_f32 v[118:119], v[54:55], v[158:159], v[108:109] op_sel_hi:[1,0,1]
	v_pk_mul_f32 v[108:109], v[164:165], v[218:219] op_sel_hi:[0,1]
	v_pk_fma_f32 v[170:171], v[174:175], v[162:163], v[170:171] op_sel_hi:[1,0,1]
	v_pk_fma_f32 v[124:125], v[178:179], v[162:163], v[124:125] op_sel_hi:[1,0,1]
	v_pk_fma_f32 v[116:117], v[182:183], v[162:163], v[116:117] op_sel_hi:[1,0,1]
	v_pk_mul_f32 v[52:53], v[168:169], v[220:221] op_sel_hi:[0,1]
	v_pk_fma_f32 v[108:109], v[118:119], v[162:163], v[108:109] op_sel_hi:[1,0,1]
	v_pk_mul_f32 v[54:55], v[168:169], v[222:223] op_sel_hi:[0,1]
	v_pk_fma_f32 v[64:65], v[148:149], v[166:167], v[64:65] op_sel_hi:[1,0,1]
	v_pk_fma_f32 v[66:67], v[150:151], v[166:167], v[66:67] op_sel_hi:[1,0,1]
	v_pk_fma_f32 v[60:61], v[170:171], v[166:167], v[60:61] op_sel_hi:[1,0,1]
	v_pk_fma_f32 v[62:63], v[172:173], v[166:167], v[62:63] op_sel_hi:[1,0,1]
	v_pk_fma_f32 v[56:57], v[124:125], v[166:167], v[56:57] op_sel_hi:[1,0,1]
	v_pk_fma_f32 v[58:59], v[126:127], v[166:167], v[58:59] op_sel_hi:[1,0,1]
	v_pk_fma_f32 v[52:53], v[116:117], v[166:167], v[52:53] op_sel_hi:[1,0,1]
	v_pk_fma_f32 v[54:55], v[108:109], v[166:167], v[54:55] op_sel_hi:[1,0,1]
	global_store_dwordx4 v[140:141], v[64:67], off offset:-32
	global_store_dwordx4 v[140:141], v[60:63], off offset:96
	global_store_dwordx4 v[140:141], v[56:59], off offset:224
	global_store_dwordx4 v[140:141], v[52:55], off offset:352
	s_and_saveexec_b64 s[16:17], vcc
	s_cbranch_execz .Lsmp_h3_743
	v_lshlrev_b32_e32 v111, 16, v209
	v_mul_f32_e32 v156, 0xbfb8aa3b, v111
	v_exp_f32_e32 v156, v156
	ds_read_b32 v158, v189
	s_waitcnt lgkmcnt(1)
	v_add_f32_e32 v2, v2, v110
	v_add_f32_e32 v156, 1.0, v156
	v_rcp_f32_e32 v156, v156
	s_waitcnt lgkmcnt(0)
	v_fmac_f32_e32 v2, s12, v158
	v_mul_f32_e32 v110, v156, v111
	v_mul_f32_e32 v2, v110, v2
	ds_write_b32 v189, v2 offset:12544

.Lsmp_h3_end:
	s_or_b64 exec, exec, s[16:17]
	s_add_i32 s13, s13, 4
	s_waitcnt lgkmcnt(0)
	s_mov_b64 s[14:15], 0x8000
	v_lshl_add_u64 v[140:141], v[140:141], 0, s[14:15]
	v_lshl_add_u64 v[144:145], v[144:145], 0, s[14:15]
	v_add_u32_e32 v185, 0x100, v185
	global_load_dwordx4 v[52:55], v[144:145], off offset:352
	global_load_dwordx4 v[56:59], v[144:145], off offset:224
	global_load_dwordx4 v[60:63], v[144:145], off offset:96
	global_load_dwordx4 v[64:67], v[144:145], off offset:-32
	s_lshl_b32 s14, s57, 5
	s_add_u32 s14, s60, s14
	s_addc_u32 s15, s61, 0
	s_nop 0
	s_load_dword s12, s[2:3], 0x10
	s_load_dword s14, s[14:15], 0x10
	v_and_b32_e32 v2, 7, v157
	v_cmp_eq_u32_e32 vcc, 4, v2
	v_add_u32_e32 v189, 0, v185
	s_waitcnt lgkmcnt(0)
	v_mov_b32_e32 v2, s14
	s_mov_b32 s14, 0x3fb8aa3b
	s_waitcnt vmcnt(24)
	v_mul_f32_e32 v68, 0x3fb8aa3b, v2
	v_fma_f32 v69, v2, s14, -v68
	v_rndne_f32_e32 v70, v68
	v_fmac_f32_e32 v69, 0x32a5705f, v2
	v_sub_f32_e32 v68, v68, v70
	v_add_f32_e32 v68, v68, v69
	v_exp_f32_e32 v68, v68
	v_cvt_i32_f32_e32 v69, v70
	s_mov_b32 s14, 0xc2ce8ed0
	v_cmp_ngt_f32_e64 s[38:39], s14, v2
	s_mov_b32 s14, 0x42b17218
	v_ldexp_f32 v68, v68, v69
	v_cndmask_b32_e64 v68, 0, v68, s[38:39]
	v_cmp_nlt_f32_e64 s[38:39], s14, v2
	s_add_i32 s14, s13, 0
	v_mov_b32_e32 v72, s14
	v_cndmask_b32_e64 v116, v203, v68, s[38:39]
	ds_read2_b32 v[68:69], v72 offset1:8
	ds_read2st64_b32 v[70:71], v189 offset1:8
	ds_read_b128 v[104:107], v137 offset:10240
	ds_read_b128 v[112:115], v137 offset:10368
	ds_read_b128 v[120:123], v137 offset:10496
	ds_read_b128 v[108:111], v137 offset:10624
	s_waitcnt lgkmcnt(5)
	v_mul_f32_e64 v2, v68, -v116
	s_waitcnt lgkmcnt(4)
	v_mul_f32_e32 v156, v68, v70
	v_mul_f32_e64 v68, v69, -v116
	v_mul_f32_e32 v68, 0x3fb8aa3b, v68
	v_exp_f32_e32 v158, v68
	v_mul_f32_e32 v160, v69, v71
	ds_read_b128 v[100:103], v137 offset:10752
	ds_read_b128 v[96:99], v137 offset:10880
	ds_read_b128 v[92:95], v137 offset:11008
	ds_read_b128 v[88:91], v137 offset:11136
	ds_read2_b32 v[68:69], v72 offset0:16 offset1:24
	v_mul_f32_e32 v2, 0x3fb8aa3b, v2
	v_exp_f32_e32 v2, v2
	s_waitcnt lgkmcnt(0)
	v_mul_f32_e64 v70, v68, -v116
	v_mul_f32_e32 v70, 0x3fb8aa3b, v70
	v_exp_f32_e32 v162, v70
	ds_read2st64_b32 v[70:71], v189 offset0:16 offset1:24
	ds_read_b128 v[84:87], v137 offset:11264
	ds_read_b128 v[80:83], v137 offset:11392
	ds_read_b128 v[76:79], v137 offset:11520
	ds_read_b128 v[72:75], v137 offset:11648
	s_waitcnt lgkmcnt(4)
	v_mul_f32_e32 v164, v68, v70
	v_mul_f32_e64 v68, v69, -v116
	v_mul_f32_e32 v68, 0x3fb8aa3b, v68
	v_exp_f32_e32 v166, v68
	v_mul_f32_e32 v168, v69, v71
	ds_read_b128 v[68:71], v137 offset:11776
	ds_read_b128 v[148:151], v137 offset:8192
	ds_read_b128 v[170:173], v137 offset:8320
	ds_read_b128 v[124:127], v137 offset:8448
	ds_read_b128 v[116:119], v137 offset:8576
	ds_read_b128 v[152:155], v137 offset:8704
	ds_read_b128 v[174:177], v137 offset:9216
	s_waitcnt lgkmcnt(5)
	v_pk_mul_f32 v[148:149], v[156:157], v[148:149] op_sel_hi:[0,1]
	v_pk_fma_f32 v[48:49], v[48:49], v[2:3], v[148:149] op_sel_hi:[1,0,1]
	s_waitcnt lgkmcnt(4)
	v_pk_mul_f32 v[170:171], v[156:157], v[170:171] op_sel_hi:[0,1]
	v_fma_f32 v210, v48, v104, 0
	v_fmac_f32_e32 v210, v49, v105
	s_waitcnt lgkmcnt(1)
	v_pk_mul_f32 v[104:105], v[160:161], v[152:153] op_sel_hi:[0,1]
	v_pk_fma_f32 v[152:153], v[48:49], v[158:159], v[104:105] op_sel_hi:[1,0,1]
	v_pk_mul_f32 v[104:105], v[156:157], v[150:151] op_sel_hi:[0,1]
	v_pk_fma_f32 v[50:51], v[50:51], v[2:3], v[104:105] op_sel_hi:[1,0,1]
	v_pk_fma_f32 v[44:45], v[44:45], v[2:3], v[170:171] op_sel_hi:[1,0,1]
	v_fmac_f32_e32 v210, v50, v106
	v_fmac_f32_e32 v210, v51, v107
	v_fmac_f32_e32 v210, v44, v112
	v_fmac_f32_e32 v210, v45, v113
	v_pk_mul_f32 v[112:113], v[156:157], v[172:173] op_sel_hi:[0,1]
	v_pk_fma_f32 v[46:47], v[46:47], v[2:3], v[112:113] op_sel_hi:[1,0,1]
	v_pk_mul_f32 v[124:125], v[156:157], v[124:125] op_sel_hi:[0,1]
	v_fmac_f32_e32 v210, v46, v114
	v_fmac_f32_e32 v210, v47, v115
	v_pk_fma_f32 v[40:41], v[40:41], v[2:3], v[124:125] op_sel_hi:[1,0,1]
	ds_read_b128 v[178:181], v137 offset:9728
	ds_read_b128 v[212:215], v137 offset:9856
	v_fmac_f32_e32 v210, v40, v120
	v_fmac_f32_e32 v210, v41, v121
	v_pk_mul_f32 v[120:121], v[156:157], v[126:127] op_sel_hi:[0,1]
	v_pk_fma_f32 v[42:43], v[42:43], v[2:3], v[120:121] op_sel_hi:[1,0,1]
	v_pk_mul_f32 v[116:117], v[156:157], v[116:117] op_sel_hi:[0,1]
	v_fmac_f32_e32 v210, v42, v122
	v_fmac_f32_e32 v210, v43, v123
	v_pk_fma_f32 v[36:37], v[36:37], v[2:3], v[116:117] op_sel_hi:[1,0,1]
	v_pk_mul_f32 v[104:105], v[160:161], v[154:155] op_sel_hi:[0,1]
	v_fmac_f32_e32 v210, v36, v108
	s_waitcnt lgkmcnt(2)
	v_pk_mul_f32 v[48:49], v[164:165], v[174:175] op_sel_hi:[0,1]
	v_pk_fma_f32 v[154:155], v[50:51], v[158:159], v[104:105] op_sel_hi:[1,0,1]
	v_pk_mul_f32 v[104:105], v[164:165], v[176:177] op_sel_hi:[0,1]
	ds_read_b128 v[174:177], v137 offset:8832
	v_fmac_f32_e32 v210, v37, v109
	v_pk_mul_f32 v[108:109], v[156:157], v[118:119] op_sel_hi:[0,1]
	v_pk_fma_f32 v[148:149], v[152:153], v[162:163], v[48:49] op_sel_hi:[1,0,1]
	s_waitcnt lgkmcnt(2)
	v_pk_mul_f32 v[48:49], v[168:169], v[178:179] op_sel_hi:[0,1]
	v_pk_mul_f32 v[50:51], v[168:169], v[180:181] op_sel_hi:[0,1]
	ds_read_b128 v[178:181], v137 offset:9344
	v_pk_fma_f32 v[38:39], v[38:39], v[2:3], v[108:109] op_sel_hi:[1,0,1]
	s_waitcnt lgkmcnt(1)
	v_pk_mul_f32 v[170:171], v[160:161], v[174:175] op_sel_hi:[0,1]
	v_fmac_f32_e32 v210, v38, v110
	v_fmac_f32_e32 v210, v39, v111
	ds_bpermute_b32 v2, v161, v210
	v_pk_mul_f32 v[112:113], v[160:161], v[176:177] op_sel_hi:[0,1]
	v_pk_fma_f32 v[174:175], v[44:45], v[158:159], v[170:171] op_sel_hi:[1,0,1]
	s_waitcnt lgkmcnt(1)
	v_pk_mul_f32 v[170:171], v[164:165], v[178:179] op_sel_hi:[0,1]
	v_pk_fma_f32 v[176:177], v[46:47], v[158:159], v[112:113] op_sel_hi:[1,0,1]
	v_pk_mul_f32 v[112:113], v[164:165], v[180:181] op_sel_hi:[0,1]
	ds_read_b128 v[178:181], v137 offset:8960
	v_pk_mul_f32 v[44:45], v[168:169], v[212:213] op_sel_hi:[0,1]
	v_pk_mul_f32 v[46:47], v[168:169], v[214:215] op_sel_hi:[0,1]
	ds_read_b128 v[212:215], v137 offset:9472
	ds_read_b128 v[216:219], v137 offset:9984
	ds_read_b128 v[220:223], v137 offset:10112
	s_waitcnt lgkmcnt(4)
	v_add_f32_e32 v2, v210, v2
	ds_bpermute_b32 v110, v163, v2
	s_waitcnt lgkmcnt(4)
	v_pk_mul_f32 v[124:125], v[160:161], v[178:179] op_sel_hi:[0,1]
	v_pk_mul_f32 v[120:121], v[160:161], v[180:181] op_sel_hi:[0,1]
	v_pk_fma_f32 v[178:179], v[40:41], v[158:159], v[124:125] op_sel_hi:[1,0,1]
	s_waitcnt lgkmcnt(3)
	v_pk_mul_f32 v[124:125], v[164:165], v[212:213] op_sel_hi:[0,1]
	v_pk_fma_f32 v[180:181], v[42:43], v[158:159], v[120:121] op_sel_hi:[1,0,1]
	v_pk_mul_f32 v[120:121], v[164:165], v[214:215] op_sel_hi:[0,1]
	ds_read_b128 v[212:215], v137 offset:9088
	s_waitcnt lgkmcnt(3)
	v_pk_mul_f32 v[40:41], v[168:169], v[216:217] op_sel_hi:[0,1]
	v_pk_mul_f32 v[42:43], v[168:169], v[218:219] op_sel_hi:[0,1]
	ds_read_b128 v[216:219], v137 offset:9600
	s_waitcnt lgkmcnt(2)
	v_add_f32_e32 v2, v2, v110
	v_pk_fma_f32 v[150:151], v[154:155], v[162:163], v[104:105] op_sel_hi:[1,0,1]
	ds_read_b128 v[104:107], v137 offset:11904
	v_pk_fma_f32 v[172:173], v[176:177], v[162:163], v[112:113] op_sel_hi:[1,0,1]
	ds_read_b128 v[112:115], v137 offset:12032
	v_pk_fma_f32 v[126:127], v[180:181], v[162:163], v[120:121] op_sel_hi:[1,0,1]
	ds_read_b128 v[120:123], v137 offset:12160
	ds_bpermute_b32 v110, v165, v2
	s_waitcnt lgkmcnt(5)
	v_pk_mul_f32 v[116:117], v[160:161], v[212:213] op_sel_hi:[0,1]
	v_pk_mul_f32 v[108:109], v[160:161], v[214:215] op_sel_hi:[0,1]
	v_pk_fma_f32 v[182:183], v[36:37], v[158:159], v[116:117] op_sel_hi:[1,0,1]
	s_waitcnt lgkmcnt(4)
	v_pk_mul_f32 v[116:117], v[164:165], v[216:217] op_sel_hi:[0,1]
	v_pk_fma_f32 v[118:119], v[38:39], v[158:159], v[108:109] op_sel_hi:[1,0,1]
	v_pk_mul_f32 v[108:109], v[164:165], v[218:219] op_sel_hi:[0,1]
	v_pk_fma_f32 v[170:171], v[174:175], v[162:163], v[170:171] op_sel_hi:[1,0,1]
	v_pk_fma_f32 v[124:125], v[178:179], v[162:163], v[124:125] op_sel_hi:[1,0,1]
	v_pk_fma_f32 v[116:117], v[182:183], v[162:163], v[116:117] op_sel_hi:[1,0,1]
	v_pk_mul_f32 v[36:37], v[168:169], v[220:221] op_sel_hi:[0,1]
	v_pk_fma_f32 v[108:109], v[118:119], v[162:163], v[108:109] op_sel_hi:[1,0,1]
	v_pk_mul_f32 v[38:39], v[168:169], v[222:223] op_sel_hi:[0,1]
	v_pk_fma_f32 v[48:49], v[148:149], v[166:167], v[48:49] op_sel_hi:[1,0,1]
	v_pk_fma_f32 v[50:51], v[150:151], v[166:167], v[50:51] op_sel_hi:[1,0,1]
	v_pk_fma_f32 v[44:45], v[170:171], v[166:167], v[44:45] op_sel_hi:[1,0,1]
	v_pk_fma_f32 v[46:47], v[172:173], v[166:167], v[46:47] op_sel_hi:[1,0,1]
	v_pk_fma_f32 v[40:41], v[124:125], v[166:167], v[40:41] op_sel_hi:[1,0,1]
	v_pk_fma_f32 v[42:43], v[126:127], v[166:167], v[42:43] op_sel_hi:[1,0,1]
	v_pk_fma_f32 v[36:37], v[116:117], v[166:167], v[36:37] op_sel_hi:[1,0,1]
	v_pk_fma_f32 v[38:39], v[108:109], v[166:167], v[38:39] op_sel_hi:[1,0,1]
	global_store_dwordx4 v[140:141], v[48:51], off offset:-32
	global_store_dwordx4 v[140:141], v[44:47], off offset:96
	global_store_dwordx4 v[140:141], v[40:43], off offset:224
	global_store_dwordx4 v[140:141], v[36:39], off offset:352
	s_and_saveexec_b64 s[16:17], vcc
	s_cbranch_execz .Lsmp_h4_743
	v_lshlrev_b32_e32 v111, 16, v209
	v_mul_f32_e32 v156, 0xbfb8aa3b, v111
	v_exp_f32_e32 v156, v156
	ds_read_b32 v158, v189
	s_waitcnt lgkmcnt(1)
	v_add_f32_e32 v2, v2, v110
	v_add_f32_e32 v156, 1.0, v156
	v_rcp_f32_e32 v156, v156
	s_waitcnt lgkmcnt(0)
	v_fmac_f32_e32 v2, s12, v158
	v_mul_f32_e32 v110, v156, v111
	v_mul_f32_e32 v2, v110, v2
	ds_write_b32 v189, v2 offset:12544

.Lsmp_h4_end:
	s_or_b64 exec, exec, s[16:17]
	s_add_i32 s13, s13, 4
	s_waitcnt lgkmcnt(0)
	s_mov_b64 s[14:15], 0x8000
	v_lshl_add_u64 v[140:141], v[140:141], 0, s[14:15]
	v_lshl_add_u64 v[144:145], v[144:145], 0, s[14:15]
	v_add_u32_e32 v185, 0x100, v185
	s_lshl_b32 s14, s57, 5
	s_add_u32 s14, s60, s14
	s_addc_u32 s15, s61, 0
	s_nop 0
	s_load_dword s12, s[2:3], 0x14
	s_load_dword s14, s[14:15], 0x14
	v_and_b32_e32 v2, 7, v157
	v_cmp_eq_u32_e32 vcc, 5, v2
	v_add_u32_e32 v189, 0, v185
	s_waitcnt lgkmcnt(0)
	v_mov_b32_e32 v2, s14
	s_mov_b32 s14, 0x3fb8aa3b
	s_waitcnt vmcnt(20)
	v_mul_f32_e32 v68, 0x3fb8aa3b, v2
	v_fma_f32 v69, v2, s14, -v68
	v_rndne_f32_e32 v70, v68
	v_fmac_f32_e32 v69, 0x32a5705f, v2
	v_sub_f32_e32 v68, v68, v70
	v_add_f32_e32 v68, v68, v69
	v_exp_f32_e32 v68, v68
	v_cvt_i32_f32_e32 v69, v70
	s_mov_b32 s14, 0xc2ce8ed0
	v_cmp_ngt_f32_e64 s[38:39], s14, v2
	s_mov_b32 s14, 0x42b17218
	v_ldexp_f32 v68, v68, v69
	v_cndmask_b32_e64 v68, 0, v68, s[38:39]
	v_cmp_nlt_f32_e64 s[38:39], s14, v2
	s_add_i32 s14, s13, 0
	v_mov_b32_e32 v72, s14
	v_cndmask_b32_e64 v116, v203, v68, s[38:39]
	ds_read2_b32 v[68:69], v72 offset1:8
	ds_read2st64_b32 v[70:71], v189 offset1:8
	ds_read_b128 v[104:107], v137 offset:10240
	ds_read_b128 v[112:115], v137 offset:10368
	ds_read_b128 v[120:123], v137 offset:10496
	ds_read_b128 v[108:111], v137 offset:10624
	s_waitcnt lgkmcnt(5)
	v_mul_f32_e64 v2, v68, -v116
	s_waitcnt lgkmcnt(4)
	v_mul_f32_e32 v156, v68, v70
	v_mul_f32_e64 v68, v69, -v116
	v_mul_f32_e32 v68, 0x3fb8aa3b, v68
	v_exp_f32_e32 v158, v68
	v_mul_f32_e32 v160, v69, v71
	ds_read_b128 v[100:103], v137 offset:10752
	ds_read_b128 v[96:99], v137 offset:10880
	ds_read_b128 v[92:95], v137 offset:11008
	ds_read_b128 v[88:91], v137 offset:11136
	ds_read2_b32 v[68:69], v72 offset0:16 offset1:24
	v_mul_f32_e32 v2, 0x3fb8aa3b, v2
	v_exp_f32_e32 v2, v2
	s_waitcnt lgkmcnt(0)
	v_mul_f32_e64 v70, v68, -v116
	v_mul_f32_e32 v70, 0x3fb8aa3b, v70
	v_exp_f32_e32 v162, v70
	ds_read2st64_b32 v[70:71], v189 offset0:16 offset1:24
	ds_read_b128 v[84:87], v137 offset:11264
	ds_read_b128 v[80:83], v137 offset:11392
	ds_read_b128 v[76:79], v137 offset:11520
	ds_read_b128 v[72:75], v137 offset:11648
	s_waitcnt lgkmcnt(4)
	v_mul_f32_e32 v164, v68, v70
	v_mul_f32_e64 v68, v69, -v116
	v_mul_f32_e32 v68, 0x3fb8aa3b, v68
	v_exp_f32_e32 v166, v68
	v_mul_f32_e32 v168, v69, v71
	ds_read_b128 v[68:71], v137 offset:11776
	ds_read_b128 v[148:151], v137 offset:8192
	ds_read_b128 v[170:173], v137 offset:8320
	ds_read_b128 v[124:127], v137 offset:8448
	ds_read_b128 v[116:119], v137 offset:8576
	ds_read_b128 v[152:155], v137 offset:8704
	ds_read_b128 v[174:177], v137 offset:9216
	s_waitcnt lgkmcnt(5)
	v_pk_mul_f32 v[148:149], v[156:157], v[148:149] op_sel_hi:[0,1]
	v_pk_fma_f32 v[12:13], v[12:13], v[2:3], v[148:149] op_sel_hi:[1,0,1]
	s_waitcnt lgkmcnt(4)
	v_pk_mul_f32 v[170:171], v[156:157], v[170:171] op_sel_hi:[0,1]
	v_fma_f32 v210, v12, v104, 0
	v_fmac_f32_e32 v210, v13, v105
	s_waitcnt lgkmcnt(1)
	v_pk_mul_f32 v[104:105], v[160:161], v[152:153] op_sel_hi:[0,1]
	v_pk_fma_f32 v[152:153], v[12:13], v[158:159], v[104:105] op_sel_hi:[1,0,1]
	v_pk_mul_f32 v[104:105], v[156:157], v[150:151] op_sel_hi:[0,1]
	v_pk_fma_f32 v[14:15], v[14:15], v[2:3], v[104:105] op_sel_hi:[1,0,1]
	v_pk_fma_f32 v[8:9], v[8:9], v[2:3], v[170:171] op_sel_hi:[1,0,1]
	v_fmac_f32_e32 v210, v14, v106
	v_fmac_f32_e32 v210, v15, v107
	v_fmac_f32_e32 v210, v8, v112
	v_fmac_f32_e32 v210, v9, v113
	v_pk_mul_f32 v[112:113], v[156:157], v[172:173] op_sel_hi:[0,1]
	v_pk_fma_f32 v[10:11], v[10:11], v[2:3], v[112:113] op_sel_hi:[1,0,1]
	v_pk_mul_f32 v[124:125], v[156:157], v[124:125] op_sel_hi:[0,1]
	v_fmac_f32_e32 v210, v10, v114
	v_fmac_f32_e32 v210, v11, v115
	v_pk_fma_f32 v[4:5], v[4:5], v[2:3], v[124:125] op_sel_hi:[1,0,1]
	ds_read_b128 v[178:181], v137 offset:9728
	ds_read_b128 v[212:215], v137 offset:9856
	v_fmac_f32_e32 v210, v4, v120
	v_fmac_f32_e32 v210, v5, v121
	v_pk_mul_f32 v[120:121], v[156:157], v[126:127] op_sel_hi:[0,1]
	v_pk_fma_f32 v[6:7], v[6:7], v[2:3], v[120:121] op_sel_hi:[1,0,1]
	v_pk_mul_f32 v[116:117], v[156:157], v[116:117] op_sel_hi:[0,1]
	v_fmac_f32_e32 v210, v6, v122
	v_fmac_f32_e32 v210, v7, v123
	v_pk_fma_f32 v[28:29], v[28:29], v[2:3], v[116:117] op_sel_hi:[1,0,1]
	v_pk_mul_f32 v[104:105], v[160:161], v[154:155] op_sel_hi:[0,1]
	v_fmac_f32_e32 v210, v28, v108
	s_waitcnt lgkmcnt(2)
	v_pk_mul_f32 v[12:13], v[164:165], v[174:175] op_sel_hi:[0,1]
	v_pk_fma_f32 v[154:155], v[14:15], v[158:159], v[104:105] op_sel_hi:[1,0,1]
	v_pk_mul_f32 v[104:105], v[164:165], v[176:177] op_sel_hi:[0,1]
	ds_read_b128 v[174:177], v137 offset:8832
	v_fmac_f32_e32 v210, v29, v109
	v_pk_mul_f32 v[108:109], v[156:157], v[118:119] op_sel_hi:[0,1]
	v_pk_fma_f32 v[148:149], v[152:153], v[162:163], v[12:13] op_sel_hi:[1,0,1]
	s_waitcnt lgkmcnt(2)
	v_pk_mul_f32 v[12:13], v[168:169], v[178:179] op_sel_hi:[0,1]
	v_pk_mul_f32 v[14:15], v[168:169], v[180:181] op_sel_hi:[0,1]
	ds_read_b128 v[178:181], v137 offset:9344
	v_pk_fma_f32 v[30:31], v[30:31], v[2:3], v[108:109] op_sel_hi:[1,0,1]
	s_waitcnt lgkmcnt(1)
	v_pk_mul_f32 v[170:171], v[160:161], v[174:175] op_sel_hi:[0,1]
	v_fmac_f32_e32 v210, v30, v110
	v_fmac_f32_e32 v210, v31, v111
	ds_bpermute_b32 v2, v161, v210
	v_pk_mul_f32 v[112:113], v[160:161], v[176:177] op_sel_hi:[0,1]
	v_pk_fma_f32 v[174:175], v[8:9], v[158:159], v[170:171] op_sel_hi:[1,0,1]
	s_waitcnt lgkmcnt(1)
	v_pk_mul_f32 v[170:171], v[164:165], v[178:179] op_sel_hi:[0,1]
	v_pk_fma_f32 v[176:177], v[10:11], v[158:159], v[112:113] op_sel_hi:[1,0,1]
	v_pk_mul_f32 v[112:113], v[164:165], v[180:181] op_sel_hi:[0,1]
	ds_read_b128 v[178:181], v137 offset:8960
	v_pk_mul_f32 v[8:9], v[168:169], v[212:213] op_sel_hi:[0,1]
	v_pk_mul_f32 v[10:11], v[168:169], v[214:215] op_sel_hi:[0,1]
	ds_read_b128 v[212:215], v137 offset:9472
	ds_read_b128 v[216:219], v137 offset:9984
	ds_read_b128 v[220:223], v137 offset:10112
	s_waitcnt lgkmcnt(4)
	v_add_f32_e32 v2, v210, v2
	ds_bpermute_b32 v110, v163, v2
	s_waitcnt lgkmcnt(4)
	v_pk_mul_f32 v[124:125], v[160:161], v[178:179] op_sel_hi:[0,1]
	v_pk_mul_f32 v[120:121], v[160:161], v[180:181] op_sel_hi:[0,1]
	v_pk_fma_f32 v[178:179], v[4:5], v[158:159], v[124:125] op_sel_hi:[1,0,1]
	s_waitcnt lgkmcnt(3)
	v_pk_mul_f32 v[124:125], v[164:165], v[212:213] op_sel_hi:[0,1]
	v_pk_fma_f32 v[180:181], v[6:7], v[158:159], v[120:121] op_sel_hi:[1,0,1]
	v_pk_mul_f32 v[120:121], v[164:165], v[214:215] op_sel_hi:[0,1]
	ds_read_b128 v[212:215], v137 offset:9088
	s_waitcnt lgkmcnt(3)
	v_pk_mul_f32 v[4:5], v[168:169], v[216:217] op_sel_hi:[0,1]
	v_pk_mul_f32 v[6:7], v[168:169], v[218:219] op_sel_hi:[0,1]
	ds_read_b128 v[216:219], v137 offset:9600
	s_waitcnt lgkmcnt(2)
	v_add_f32_e32 v2, v2, v110
	v_pk_fma_f32 v[150:151], v[154:155], v[162:163], v[104:105] op_sel_hi:[1,0,1]
	ds_read_b128 v[104:107], v137 offset:11904
	v_pk_fma_f32 v[172:173], v[176:177], v[162:163], v[112:113] op_sel_hi:[1,0,1]
	ds_read_b128 v[112:115], v137 offset:12032
	v_pk_fma_f32 v[126:127], v[180:181], v[162:163], v[120:121] op_sel_hi:[1,0,1]
	ds_read_b128 v[120:123], v137 offset:12160
	ds_bpermute_b32 v110, v165, v2
	s_waitcnt lgkmcnt(5)
	v_pk_mul_f32 v[116:117], v[160:161], v[212:213] op_sel_hi:[0,1]
	v_pk_mul_f32 v[108:109], v[160:161], v[214:215] op_sel_hi:[0,1]
	v_pk_fma_f32 v[182:183], v[28:29], v[158:159], v[116:117] op_sel_hi:[1,0,1]
	s_waitcnt lgkmcnt(4)
	v_pk_mul_f32 v[116:117], v[164:165], v[216:217] op_sel_hi:[0,1]
	v_pk_fma_f32 v[118:119], v[30:31], v[158:159], v[108:109] op_sel_hi:[1,0,1]
	v_pk_mul_f32 v[108:109], v[164:165], v[218:219] op_sel_hi:[0,1]
	v_pk_fma_f32 v[170:171], v[174:175], v[162:163], v[170:171] op_sel_hi:[1,0,1]
	v_pk_fma_f32 v[124:125], v[178:179], v[162:163], v[124:125] op_sel_hi:[1,0,1]
	v_pk_fma_f32 v[116:117], v[182:183], v[162:163], v[116:117] op_sel_hi:[1,0,1]
	v_pk_mul_f32 v[28:29], v[168:169], v[220:221] op_sel_hi:[0,1]
	v_pk_fma_f32 v[108:109], v[118:119], v[162:163], v[108:109] op_sel_hi:[1,0,1]
	v_pk_mul_f32 v[30:31], v[168:169], v[222:223] op_sel_hi:[0,1]
	v_pk_fma_f32 v[12:13], v[148:149], v[166:167], v[12:13] op_sel_hi:[1,0,1]
	v_pk_fma_f32 v[14:15], v[150:151], v[166:167], v[14:15] op_sel_hi:[1,0,1]
	v_pk_fma_f32 v[8:9], v[170:171], v[166:167], v[8:9] op_sel_hi:[1,0,1]
	v_pk_fma_f32 v[10:11], v[172:173], v[166:167], v[10:11] op_sel_hi:[1,0,1]
	v_pk_fma_f32 v[4:5], v[124:125], v[166:167], v[4:5] op_sel_hi:[1,0,1]
	v_pk_fma_f32 v[6:7], v[126:127], v[166:167], v[6:7] op_sel_hi:[1,0,1]
	v_pk_fma_f32 v[28:29], v[116:117], v[166:167], v[28:29] op_sel_hi:[1,0,1]
	v_pk_fma_f32 v[30:31], v[108:109], v[166:167], v[30:31] op_sel_hi:[1,0,1]
	global_store_dwordx4 v[140:141], v[12:15], off offset:-32
	global_store_dwordx4 v[140:141], v[8:11], off offset:96
	global_store_dwordx4 v[140:141], v[4:7], off offset:224
	global_store_dwordx4 v[140:141], v[28:31], off offset:352
	s_and_saveexec_b64 s[16:17], vcc
	s_cbranch_execz .Lsmp_h5_743
	v_lshlrev_b32_e32 v111, 16, v209
	v_mul_f32_e32 v156, 0xbfb8aa3b, v111
	v_exp_f32_e32 v156, v156
	ds_read_b32 v158, v189
	s_waitcnt lgkmcnt(1)
	v_add_f32_e32 v2, v2, v110
	v_add_f32_e32 v156, 1.0, v156
	v_rcp_f32_e32 v156, v156
	s_waitcnt lgkmcnt(0)
	v_fmac_f32_e32 v2, s12, v158
	v_mul_f32_e32 v110, v156, v111
	v_mul_f32_e32 v2, v110, v2
	ds_write_b32 v189, v2 offset:12544

.Lsmp_h5_end:
	s_or_b64 exec, exec, s[16:17]
	s_add_i32 s13, s13, 4
	s_waitcnt lgkmcnt(0)
	s_mov_b64 s[14:15], 0x8000
	v_lshl_add_u64 v[140:141], v[140:141], 0, s[14:15]
	v_lshl_add_u64 v[144:145], v[144:145], 0, s[14:15]
	v_add_u32_e32 v185, 0x100, v185
	s_lshl_b32 s14, s57, 5
	s_add_u32 s14, s60, s14
	s_addc_u32 s15, s61, 0
	s_nop 0
	s_load_dword s12, s[2:3], 0x18
	s_load_dword s14, s[14:15], 0x18
	v_and_b32_e32 v2, 7, v157
	v_cmp_eq_u32_e32 vcc, 6, v2
	v_add_u32_e32 v189, 0, v185
	s_waitcnt lgkmcnt(0)
	v_mov_b32_e32 v2, s14
	s_mov_b32 s14, 0x3fb8aa3b
	s_waitcnt vmcnt(16)
	v_mul_f32_e32 v68, 0x3fb8aa3b, v2
	v_fma_f32 v69, v2, s14, -v68
	v_rndne_f32_e32 v70, v68
	v_fmac_f32_e32 v69, 0x32a5705f, v2
	v_sub_f32_e32 v68, v68, v70
	v_add_f32_e32 v68, v68, v69
	v_exp_f32_e32 v68, v68
	v_cvt_i32_f32_e32 v69, v70
	s_mov_b32 s14, 0xc2ce8ed0
	v_cmp_ngt_f32_e64 s[38:39], s14, v2
	s_mov_b32 s14, 0x42b17218
	v_ldexp_f32 v68, v68, v69
	v_cndmask_b32_e64 v68, 0, v68, s[38:39]
	v_cmp_nlt_f32_e64 s[38:39], s14, v2
	s_add_i32 s14, s13, 0
	v_mov_b32_e32 v72, s14
	v_cndmask_b32_e64 v116, v203, v68, s[38:39]
	ds_read2_b32 v[68:69], v72 offset1:8
	ds_read2st64_b32 v[70:71], v189 offset1:8
	ds_read_b128 v[104:107], v137 offset:10240
	ds_read_b128 v[112:115], v137 offset:10368
	ds_read_b128 v[120:123], v137 offset:10496
	ds_read_b128 v[108:111], v137 offset:10624
	s_waitcnt lgkmcnt(5)
	v_mul_f32_e64 v2, v68, -v116
	s_waitcnt lgkmcnt(4)
	v_mul_f32_e32 v156, v68, v70
	v_mul_f32_e64 v68, v69, -v116
	v_mul_f32_e32 v68, 0x3fb8aa3b, v68
	v_exp_f32_e32 v158, v68
	v_mul_f32_e32 v160, v69, v71
	ds_read_b128 v[100:103], v137 offset:10752
	ds_read_b128 v[96:99], v137 offset:10880
	ds_read_b128 v[92:95], v137 offset:11008
	ds_read_b128 v[88:91], v137 offset:11136
	ds_read2_b32 v[68:69], v72 offset0:16 offset1:24
	v_mul_f32_e32 v2, 0x3fb8aa3b, v2
	v_exp_f32_e32 v2, v2
	s_waitcnt lgkmcnt(0)
	v_mul_f32_e64 v70, v68, -v116
	v_mul_f32_e32 v70, 0x3fb8aa3b, v70
	v_exp_f32_e32 v162, v70
	ds_read2st64_b32 v[70:71], v189 offset0:16 offset1:24
	ds_read_b128 v[84:87], v137 offset:11264
	ds_read_b128 v[80:83], v137 offset:11392
	ds_read_b128 v[76:79], v137 offset:11520
	ds_read_b128 v[72:75], v137 offset:11648
	s_waitcnt lgkmcnt(4)
	v_mul_f32_e32 v164, v68, v70
	v_mul_f32_e64 v68, v69, -v116
	v_mul_f32_e32 v68, 0x3fb8aa3b, v68
	v_exp_f32_e32 v166, v68
	v_mul_f32_e32 v168, v69, v71
	ds_read_b128 v[68:71], v137 offset:11776
	ds_read_b128 v[148:151], v137 offset:8192
	ds_read_b128 v[170:173], v137 offset:8320
	ds_read_b128 v[124:127], v137 offset:8448
	ds_read_b128 v[116:119], v137 offset:8576
	ds_read_b128 v[152:155], v137 offset:8704
	ds_read_b128 v[174:177], v137 offset:9216
	s_waitcnt lgkmcnt(5)
	v_pk_mul_f32 v[148:149], v[156:157], v[148:149] op_sel_hi:[0,1]
	v_pk_fma_f32 v[16:17], v[16:17], v[2:3], v[148:149] op_sel_hi:[1,0,1]
	s_waitcnt lgkmcnt(4)
	v_pk_mul_f32 v[170:171], v[156:157], v[170:171] op_sel_hi:[0,1]
	v_fma_f32 v210, v16, v104, 0
	v_fmac_f32_e32 v210, v17, v105
	s_waitcnt lgkmcnt(1)
	v_pk_mul_f32 v[104:105], v[160:161], v[152:153] op_sel_hi:[0,1]
	v_pk_fma_f32 v[152:153], v[16:17], v[158:159], v[104:105] op_sel_hi:[1,0,1]
	v_pk_mul_f32 v[104:105], v[156:157], v[150:151] op_sel_hi:[0,1]
	v_pk_fma_f32 v[18:19], v[18:19], v[2:3], v[104:105] op_sel_hi:[1,0,1]
	v_pk_fma_f32 v[32:33], v[32:33], v[2:3], v[170:171] op_sel_hi:[1,0,1]
	v_fmac_f32_e32 v210, v18, v106
	v_fmac_f32_e32 v210, v19, v107
	v_fmac_f32_e32 v210, v32, v112
	v_fmac_f32_e32 v210, v33, v113
	v_pk_mul_f32 v[112:113], v[156:157], v[172:173] op_sel_hi:[0,1]
	v_pk_fma_f32 v[34:35], v[34:35], v[2:3], v[112:113] op_sel_hi:[1,0,1]
	v_pk_mul_f32 v[124:125], v[156:157], v[124:125] op_sel_hi:[0,1]
	v_fmac_f32_e32 v210, v34, v114
	v_fmac_f32_e32 v210, v35, v115
	v_pk_fma_f32 v[24:25], v[24:25], v[2:3], v[124:125] op_sel_hi:[1,0,1]
	ds_read_b128 v[178:181], v137 offset:9728
	ds_read_b128 v[212:215], v137 offset:9856
	v_fmac_f32_e32 v210, v24, v120
	v_fmac_f32_e32 v210, v25, v121
	v_pk_mul_f32 v[120:121], v[156:157], v[126:127] op_sel_hi:[0,1]
	v_pk_fma_f32 v[26:27], v[26:27], v[2:3], v[120:121] op_sel_hi:[1,0,1]
	v_pk_mul_f32 v[116:117], v[156:157], v[116:117] op_sel_hi:[0,1]
	v_fmac_f32_e32 v210, v26, v122
	v_fmac_f32_e32 v210, v27, v123
	v_pk_fma_f32 v[20:21], v[20:21], v[2:3], v[116:117] op_sel_hi:[1,0,1]
	v_pk_mul_f32 v[104:105], v[160:161], v[154:155] op_sel_hi:[0,1]
	v_fmac_f32_e32 v210, v20, v108
	s_waitcnt lgkmcnt(2)
	v_pk_mul_f32 v[16:17], v[164:165], v[174:175] op_sel_hi:[0,1]
	v_pk_fma_f32 v[154:155], v[18:19], v[158:159], v[104:105] op_sel_hi:[1,0,1]
	v_pk_mul_f32 v[104:105], v[164:165], v[176:177] op_sel_hi:[0,1]
	ds_read_b128 v[174:177], v137 offset:8832
	v_fmac_f32_e32 v210, v21, v109
	v_pk_mul_f32 v[108:109], v[156:157], v[118:119] op_sel_hi:[0,1]
	v_pk_fma_f32 v[148:149], v[152:153], v[162:163], v[16:17] op_sel_hi:[1,0,1]
	s_waitcnt lgkmcnt(2)
	v_pk_mul_f32 v[16:17], v[168:169], v[178:179] op_sel_hi:[0,1]
	v_pk_mul_f32 v[18:19], v[168:169], v[180:181] op_sel_hi:[0,1]
	ds_read_b128 v[178:181], v137 offset:9344
	v_pk_fma_f32 v[22:23], v[22:23], v[2:3], v[108:109] op_sel_hi:[1,0,1]
	s_waitcnt lgkmcnt(1)
	v_pk_mul_f32 v[170:171], v[160:161], v[174:175] op_sel_hi:[0,1]
	v_fmac_f32_e32 v210, v22, v110
	v_fmac_f32_e32 v210, v23, v111
	ds_bpermute_b32 v2, v161, v210
	v_pk_mul_f32 v[112:113], v[160:161], v[176:177] op_sel_hi:[0,1]
	v_pk_fma_f32 v[174:175], v[32:33], v[158:159], v[170:171] op_sel_hi:[1,0,1]
	s_waitcnt lgkmcnt(1)
	v_pk_mul_f32 v[170:171], v[164:165], v[178:179] op_sel_hi:[0,1]
	v_pk_fma_f32 v[176:177], v[34:35], v[158:159], v[112:113] op_sel_hi:[1,0,1]
	v_pk_mul_f32 v[112:113], v[164:165], v[180:181] op_sel_hi:[0,1]
	ds_read_b128 v[178:181], v137 offset:8960
	v_pk_mul_f32 v[32:33], v[168:169], v[212:213] op_sel_hi:[0,1]
	v_pk_mul_f32 v[34:35], v[168:169], v[214:215] op_sel_hi:[0,1]
	ds_read_b128 v[212:215], v137 offset:9472
	ds_read_b128 v[216:219], v137 offset:9984
	ds_read_b128 v[220:223], v137 offset:10112
	s_waitcnt lgkmcnt(4)
	v_add_f32_e32 v2, v210, v2
	ds_bpermute_b32 v110, v163, v2
	s_waitcnt lgkmcnt(4)
	v_pk_mul_f32 v[124:125], v[160:161], v[178:179] op_sel_hi:[0,1]
	v_pk_mul_f32 v[120:121], v[160:161], v[180:181] op_sel_hi:[0,1]
	v_pk_fma_f32 v[178:179], v[24:25], v[158:159], v[124:125] op_sel_hi:[1,0,1]
	s_waitcnt lgkmcnt(3)
	v_pk_mul_f32 v[124:125], v[164:165], v[212:213] op_sel_hi:[0,1]
	v_pk_fma_f32 v[180:181], v[26:27], v[158:159], v[120:121] op_sel_hi:[1,0,1]
	v_pk_mul_f32 v[120:121], v[164:165], v[214:215] op_sel_hi:[0,1]
	ds_read_b128 v[212:215], v137 offset:9088
	s_waitcnt lgkmcnt(3)
	v_pk_mul_f32 v[24:25], v[168:169], v[216:217] op_sel_hi:[0,1]
	v_pk_mul_f32 v[26:27], v[168:169], v[218:219] op_sel_hi:[0,1]
	ds_read_b128 v[216:219], v137 offset:9600
	s_waitcnt lgkmcnt(2)
	v_add_f32_e32 v2, v2, v110
	v_pk_fma_f32 v[150:151], v[154:155], v[162:163], v[104:105] op_sel_hi:[1,0,1]
	ds_read_b128 v[104:107], v137 offset:11904
	v_pk_fma_f32 v[172:173], v[176:177], v[162:163], v[112:113] op_sel_hi:[1,0,1]
	ds_read_b128 v[112:115], v137 offset:12032
	v_pk_fma_f32 v[126:127], v[180:181], v[162:163], v[120:121] op_sel_hi:[1,0,1]
	ds_read_b128 v[120:123], v137 offset:12160
	ds_bpermute_b32 v110, v165, v2
	s_waitcnt lgkmcnt(5)
	v_pk_mul_f32 v[116:117], v[160:161], v[212:213] op_sel_hi:[0,1]
	v_pk_mul_f32 v[108:109], v[160:161], v[214:215] op_sel_hi:[0,1]
	v_pk_fma_f32 v[182:183], v[20:21], v[158:159], v[116:117] op_sel_hi:[1,0,1]
	s_waitcnt lgkmcnt(4)
	v_pk_mul_f32 v[116:117], v[164:165], v[216:217] op_sel_hi:[0,1]
	v_pk_fma_f32 v[118:119], v[22:23], v[158:159], v[108:109] op_sel_hi:[1,0,1]
	v_pk_mul_f32 v[108:109], v[164:165], v[218:219] op_sel_hi:[0,1]
	v_pk_fma_f32 v[170:171], v[174:175], v[162:163], v[170:171] op_sel_hi:[1,0,1]
	v_pk_fma_f32 v[124:125], v[178:179], v[162:163], v[124:125] op_sel_hi:[1,0,1]
	v_pk_fma_f32 v[116:117], v[182:183], v[162:163], v[116:117] op_sel_hi:[1,0,1]
	v_pk_mul_f32 v[20:21], v[168:169], v[220:221] op_sel_hi:[0,1]
	v_pk_fma_f32 v[108:109], v[118:119], v[162:163], v[108:109] op_sel_hi:[1,0,1]
	v_pk_mul_f32 v[22:23], v[168:169], v[222:223] op_sel_hi:[0,1]
	v_pk_fma_f32 v[16:17], v[148:149], v[166:167], v[16:17] op_sel_hi:[1,0,1]
	v_pk_fma_f32 v[18:19], v[150:151], v[166:167], v[18:19] op_sel_hi:[1,0,1]
	v_pk_fma_f32 v[32:33], v[170:171], v[166:167], v[32:33] op_sel_hi:[1,0,1]
	v_pk_fma_f32 v[34:35], v[172:173], v[166:167], v[34:35] op_sel_hi:[1,0,1]
	v_pk_fma_f32 v[24:25], v[124:125], v[166:167], v[24:25] op_sel_hi:[1,0,1]
	v_pk_fma_f32 v[26:27], v[126:127], v[166:167], v[26:27] op_sel_hi:[1,0,1]
	v_pk_fma_f32 v[20:21], v[116:117], v[166:167], v[20:21] op_sel_hi:[1,0,1]
	v_pk_fma_f32 v[22:23], v[108:109], v[166:167], v[22:23] op_sel_hi:[1,0,1]
	global_store_dwordx4 v[140:141], v[16:19], off offset:-32
	global_store_dwordx4 v[140:141], v[32:35], off offset:96
	global_store_dwordx4 v[140:141], v[24:27], off offset:224
	global_store_dwordx4 v[140:141], v[20:23], off offset:352
	s_and_saveexec_b64 s[16:17], vcc
	s_cbranch_execz .Lsmp_h6_743
	v_lshlrev_b32_e32 v111, 16, v209
	v_mul_f32_e32 v156, 0xbfb8aa3b, v111
	v_exp_f32_e32 v156, v156
	ds_read_b32 v158, v189
	s_waitcnt lgkmcnt(1)
	v_add_f32_e32 v2, v2, v110
	v_add_f32_e32 v156, 1.0, v156
	v_rcp_f32_e32 v156, v156
	s_waitcnt lgkmcnt(0)
	v_fmac_f32_e32 v2, s12, v158
	v_mul_f32_e32 v110, v156, v111
	v_mul_f32_e32 v2, v110, v2
	ds_write_b32 v189, v2 offset:12544

.Lsmp_h6_end:
	s_or_b64 exec, exec, s[16:17]
	s_add_i32 s13, s13, 4
	s_waitcnt lgkmcnt(0)
	s_mov_b64 s[14:15], 0x8000
	v_lshl_add_u64 v[140:141], v[140:141], 0, s[14:15]
	v_lshl_add_u64 v[144:145], v[144:145], 0, s[14:15]
	v_add_u32_e32 v185, 0x100, v185
	s_lshl_b32 s14, s57, 5
	s_add_u32 s14, s60, s14
	s_addc_u32 s15, s61, 0
	s_nop 0
	s_load_dword s12, s[2:3], 0x1c
	s_load_dword s14, s[14:15], 0x1c
	v_and_b32_e32 v2, 7, v157
	v_cmp_eq_u32_e32 vcc, 7, v2
	v_add_u32_e32 v189, 0, v185
	s_waitcnt lgkmcnt(0)
	v_mov_b32_e32 v2, s14
	s_mov_b32 s14, 0x3fb8aa3b
	s_waitcnt vmcnt(12)
	v_mul_f32_e32 v68, 0x3fb8aa3b, v2
	v_fma_f32 v69, v2, s14, -v68
	v_rndne_f32_e32 v70, v68
	v_fmac_f32_e32 v69, 0x32a5705f, v2
	v_sub_f32_e32 v68, v68, v70
	v_add_f32_e32 v68, v68, v69
	v_exp_f32_e32 v68, v68
	v_cvt_i32_f32_e32 v69, v70
	s_mov_b32 s14, 0xc2ce8ed0
	v_cmp_ngt_f32_e64 s[38:39], s14, v2
	s_mov_b32 s14, 0x42b17218
	v_ldexp_f32 v68, v68, v69
	v_cndmask_b32_e64 v68, 0, v68, s[38:39]
	v_cmp_nlt_f32_e64 s[38:39], s14, v2
	s_add_i32 s14, s13, 0
	v_mov_b32_e32 v72, s14
	v_cndmask_b32_e64 v116, v203, v68, s[38:39]
	ds_read2_b32 v[68:69], v72 offset1:8
	ds_read2st64_b32 v[70:71], v189 offset1:8
	ds_read_b128 v[104:107], v137 offset:10240
	ds_read_b128 v[112:115], v137 offset:10368
	ds_read_b128 v[120:123], v137 offset:10496
	ds_read_b128 v[108:111], v137 offset:10624
	s_waitcnt lgkmcnt(5)
	v_mul_f32_e64 v2, v68, -v116
	s_waitcnt lgkmcnt(4)
	v_mul_f32_e32 v156, v68, v70
	v_mul_f32_e64 v68, v69, -v116
	v_mul_f32_e32 v68, 0x3fb8aa3b, v68
	v_exp_f32_e32 v158, v68
	v_mul_f32_e32 v160, v69, v71
	ds_read_b128 v[100:103], v137 offset:10752
	ds_read_b128 v[96:99], v137 offset:10880
	ds_read_b128 v[92:95], v137 offset:11008
	ds_read_b128 v[88:91], v137 offset:11136
	ds_read2_b32 v[68:69], v72 offset0:16 offset1:24
	v_mul_f32_e32 v2, 0x3fb8aa3b, v2
	v_exp_f32_e32 v2, v2
	s_waitcnt lgkmcnt(0)
	v_mul_f32_e64 v70, v68, -v116
	v_mul_f32_e32 v70, 0x3fb8aa3b, v70
	v_exp_f32_e32 v162, v70
	ds_read2st64_b32 v[70:71], v189 offset0:16 offset1:24
	ds_read_b128 v[84:87], v137 offset:11264
	ds_read_b128 v[80:83], v137 offset:11392
	ds_read_b128 v[76:79], v137 offset:11520
	ds_read_b128 v[72:75], v137 offset:11648
	s_waitcnt lgkmcnt(4)
	v_mul_f32_e32 v164, v68, v70
	v_mul_f32_e64 v68, v69, -v116
	v_mul_f32_e32 v68, 0x3fb8aa3b, v68
	v_exp_f32_e32 v166, v68
	v_mul_f32_e32 v168, v69, v71
	ds_read_b128 v[68:71], v137 offset:11776
	ds_read_b128 v[148:151], v137 offset:8192
	ds_read_b128 v[170:173], v137 offset:8320
	ds_read_b128 v[124:127], v137 offset:8448
	ds_read_b128 v[116:119], v137 offset:8576
	ds_read_b128 v[152:155], v137 offset:8704
	ds_read_b128 v[174:177], v137 offset:9216
	s_waitcnt lgkmcnt(5)
	v_pk_mul_f32 v[148:149], v[156:157], v[148:149] op_sel_hi:[0,1]
	v_pk_fma_f32 v[64:65], v[64:65], v[2:3], v[148:149] op_sel_hi:[1,0,1]
	s_waitcnt lgkmcnt(4)
	v_pk_mul_f32 v[170:171], v[156:157], v[170:171] op_sel_hi:[0,1]
	v_fma_f32 v210, v64, v104, 0
	v_fmac_f32_e32 v210, v65, v105
	s_waitcnt lgkmcnt(1)
	v_pk_mul_f32 v[104:105], v[160:161], v[152:153] op_sel_hi:[0,1]
	v_pk_fma_f32 v[152:153], v[64:65], v[158:159], v[104:105] op_sel_hi:[1,0,1]
	v_pk_mul_f32 v[104:105], v[156:157], v[150:151] op_sel_hi:[0,1]
	v_pk_fma_f32 v[66:67], v[66:67], v[2:3], v[104:105] op_sel_hi:[1,0,1]
	v_pk_fma_f32 v[60:61], v[60:61], v[2:3], v[170:171] op_sel_hi:[1,0,1]
	v_fmac_f32_e32 v210, v66, v106
	v_fmac_f32_e32 v210, v67, v107
	v_fmac_f32_e32 v210, v60, v112
	v_fmac_f32_e32 v210, v61, v113
	v_pk_mul_f32 v[112:113], v[156:157], v[172:173] op_sel_hi:[0,1]
	v_pk_fma_f32 v[62:63], v[62:63], v[2:3], v[112:113] op_sel_hi:[1,0,1]
	v_pk_mul_f32 v[124:125], v[156:157], v[124:125] op_sel_hi:[0,1]
	v_fmac_f32_e32 v210, v62, v114
	v_fmac_f32_e32 v210, v63, v115
	v_pk_fma_f32 v[56:57], v[56:57], v[2:3], v[124:125] op_sel_hi:[1,0,1]
	ds_read_b128 v[178:181], v137 offset:9728
	ds_read_b128 v[212:215], v137 offset:9856
	v_fmac_f32_e32 v210, v56, v120
	v_fmac_f32_e32 v210, v57, v121
	v_pk_mul_f32 v[120:121], v[156:157], v[126:127] op_sel_hi:[0,1]
	v_pk_fma_f32 v[58:59], v[58:59], v[2:3], v[120:121] op_sel_hi:[1,0,1]
	v_pk_mul_f32 v[116:117], v[156:157], v[116:117] op_sel_hi:[0,1]
	v_fmac_f32_e32 v210, v58, v122
	v_fmac_f32_e32 v210, v59, v123
	v_pk_fma_f32 v[52:53], v[52:53], v[2:3], v[116:117] op_sel_hi:[1,0,1]
	v_pk_mul_f32 v[104:105], v[160:161], v[154:155] op_sel_hi:[0,1]
	v_fmac_f32_e32 v210, v52, v108
	s_waitcnt lgkmcnt(2)
	v_pk_mul_f32 v[64:65], v[164:165], v[174:175] op_sel_hi:[0,1]
	v_pk_fma_f32 v[154:155], v[66:67], v[158:159], v[104:105] op_sel_hi:[1,0,1]
	v_pk_mul_f32 v[104:105], v[164:165], v[176:177] op_sel_hi:[0,1]
	ds_read_b128 v[174:177], v137 offset:8832
	v_fmac_f32_e32 v210, v53, v109
	v_pk_mul_f32 v[108:109], v[156:157], v[118:119] op_sel_hi:[0,1]
	v_pk_fma_f32 v[148:149], v[152:153], v[162:163], v[64:65] op_sel_hi:[1,0,1]
	s_waitcnt lgkmcnt(2)
	v_pk_mul_f32 v[64:65], v[168:169], v[178:179] op_sel_hi:[0,1]
	v_pk_mul_f32 v[66:67], v[168:169], v[180:181] op_sel_hi:[0,1]
	ds_read_b128 v[178:181], v137 offset:9344
	v_pk_fma_f32 v[54:55], v[54:55], v[2:3], v[108:109] op_sel_hi:[1,0,1]
	s_waitcnt lgkmcnt(1)
	v_pk_mul_f32 v[170:171], v[160:161], v[174:175] op_sel_hi:[0,1]
	v_fmac_f32_e32 v210, v54, v110
	v_fmac_f32_e32 v210, v55, v111
	ds_bpermute_b32 v2, v161, v210
	v_pk_mul_f32 v[112:113], v[160:161], v[176:177] op_sel_hi:[0,1]
	v_pk_fma_f32 v[174:175], v[60:61], v[158:159], v[170:171] op_sel_hi:[1,0,1]
	s_waitcnt lgkmcnt(1)
	v_pk_mul_f32 v[170:171], v[164:165], v[178:179] op_sel_hi:[0,1]
	v_pk_fma_f32 v[176:177], v[62:63], v[158:159], v[112:113] op_sel_hi:[1,0,1]
	v_pk_mul_f32 v[112:113], v[164:165], v[180:181] op_sel_hi:[0,1]
	ds_read_b128 v[178:181], v137 offset:8960
	v_pk_mul_f32 v[60:61], v[168:169], v[212:213] op_sel_hi:[0,1]
	v_pk_mul_f32 v[62:63], v[168:169], v[214:215] op_sel_hi:[0,1]
	ds_read_b128 v[212:215], v137 offset:9472
	ds_read_b128 v[216:219], v137 offset:9984
	ds_read_b128 v[220:223], v137 offset:10112
	s_waitcnt lgkmcnt(4)
	v_add_f32_e32 v2, v210, v2
	ds_bpermute_b32 v110, v163, v2
	s_waitcnt lgkmcnt(4)
	v_pk_mul_f32 v[124:125], v[160:161], v[178:179] op_sel_hi:[0,1]
	v_pk_mul_f32 v[120:121], v[160:161], v[180:181] op_sel_hi:[0,1]
	v_pk_fma_f32 v[178:179], v[56:57], v[158:159], v[124:125] op_sel_hi:[1,0,1]
	s_waitcnt lgkmcnt(3)
	v_pk_mul_f32 v[124:125], v[164:165], v[212:213] op_sel_hi:[0,1]
	v_pk_fma_f32 v[180:181], v[58:59], v[158:159], v[120:121] op_sel_hi:[1,0,1]
	v_pk_mul_f32 v[120:121], v[164:165], v[214:215] op_sel_hi:[0,1]
	ds_read_b128 v[212:215], v137 offset:9088
	s_waitcnt lgkmcnt(3)
	v_pk_mul_f32 v[56:57], v[168:169], v[216:217] op_sel_hi:[0,1]
	v_pk_mul_f32 v[58:59], v[168:169], v[218:219] op_sel_hi:[0,1]
	ds_read_b128 v[216:219], v137 offset:9600
	s_waitcnt lgkmcnt(2)
	v_add_f32_e32 v2, v2, v110
	v_pk_fma_f32 v[150:151], v[154:155], v[162:163], v[104:105] op_sel_hi:[1,0,1]
	ds_read_b128 v[104:107], v137 offset:11904
	v_pk_fma_f32 v[172:173], v[176:177], v[162:163], v[112:113] op_sel_hi:[1,0,1]
	ds_read_b128 v[112:115], v137 offset:12032
	v_pk_fma_f32 v[126:127], v[180:181], v[162:163], v[120:121] op_sel_hi:[1,0,1]
	ds_read_b128 v[120:123], v137 offset:12160
	ds_bpermute_b32 v110, v165, v2
	s_waitcnt lgkmcnt(5)
	v_pk_mul_f32 v[116:117], v[160:161], v[212:213] op_sel_hi:[0,1]
	v_pk_mul_f32 v[108:109], v[160:161], v[214:215] op_sel_hi:[0,1]
	v_pk_fma_f32 v[182:183], v[52:53], v[158:159], v[116:117] op_sel_hi:[1,0,1]
	s_waitcnt lgkmcnt(4)
	v_pk_mul_f32 v[116:117], v[164:165], v[216:217] op_sel_hi:[0,1]
	v_pk_fma_f32 v[118:119], v[54:55], v[158:159], v[108:109] op_sel_hi:[1,0,1]
	v_pk_mul_f32 v[108:109], v[164:165], v[218:219] op_sel_hi:[0,1]
	v_pk_fma_f32 v[170:171], v[174:175], v[162:163], v[170:171] op_sel_hi:[1,0,1]
	v_pk_fma_f32 v[124:125], v[178:179], v[162:163], v[124:125] op_sel_hi:[1,0,1]
	v_pk_fma_f32 v[116:117], v[182:183], v[162:163], v[116:117] op_sel_hi:[1,0,1]
	v_pk_mul_f32 v[52:53], v[168:169], v[220:221] op_sel_hi:[0,1]
	v_pk_fma_f32 v[108:109], v[118:119], v[162:163], v[108:109] op_sel_hi:[1,0,1]
	v_pk_mul_f32 v[54:55], v[168:169], v[222:223] op_sel_hi:[0,1]
	v_pk_fma_f32 v[64:65], v[148:149], v[166:167], v[64:65] op_sel_hi:[1,0,1]
	v_pk_fma_f32 v[66:67], v[150:151], v[166:167], v[66:67] op_sel_hi:[1,0,1]
	v_pk_fma_f32 v[60:61], v[170:171], v[166:167], v[60:61] op_sel_hi:[1,0,1]
	v_pk_fma_f32 v[62:63], v[172:173], v[166:167], v[62:63] op_sel_hi:[1,0,1]
	v_pk_fma_f32 v[56:57], v[124:125], v[166:167], v[56:57] op_sel_hi:[1,0,1]
	v_pk_fma_f32 v[58:59], v[126:127], v[166:167], v[58:59] op_sel_hi:[1,0,1]
	v_pk_fma_f32 v[52:53], v[116:117], v[166:167], v[52:53] op_sel_hi:[1,0,1]
	v_pk_fma_f32 v[54:55], v[108:109], v[166:167], v[54:55] op_sel_hi:[1,0,1]
	global_store_dwordx4 v[140:141], v[64:67], off offset:-32
	global_store_dwordx4 v[140:141], v[60:63], off offset:96
	global_store_dwordx4 v[140:141], v[56:59], off offset:224
	global_store_dwordx4 v[140:141], v[52:55], off offset:352
	s_and_saveexec_b64 s[16:17], vcc
	s_cbranch_execz .Lsmp_h7_743
	v_lshlrev_b32_e32 v111, 16, v209
	v_mul_f32_e32 v156, 0xbfb8aa3b, v111
	v_exp_f32_e32 v156, v156
	ds_read_b32 v158, v189
	s_waitcnt lgkmcnt(1)
	v_add_f32_e32 v2, v2, v110
	v_add_f32_e32 v156, 1.0, v156
	v_rcp_f32_e32 v156, v156
	s_waitcnt lgkmcnt(0)
	v_fmac_f32_e32 v2, s12, v158
	v_mul_f32_e32 v110, v156, v111
	v_mul_f32_e32 v2, v110, v2
	ds_write_b32 v189, v2 offset:12544
